# A/B: all s_setprio flips in the GEMM K-loops deleted
# speedup vs baseline: 1.0030x; 1.0026x over previous
; #define PG8_STAGE(bufoff, gbase, voff) do { _Pragma("unroll") for (int _i = 0; _i < 2; ++_i) \
;         __builtin_amdgcn_global_load_lds((const unsigned*)((const char*)(gbase) + (voff)[_i]), (LAS unsigned*)(lds + (bufoff) + ldsw + _i * 8192), 16, 0, 0); } while (0)
; #define PG8_LDA(dst, b, h) do { _Pragma("unroll") for (int m = 0; m < 4; ++m) _Pragma("unroll") for (int k = 0; k < 2; ++k) dst[m][k] = *(const LAS bf16x8*)(lds + PG8_SA(b, h) + aoff + m * 2048 + k * 1024); } while (0)
; #define PG8_LDB(dst, b, h) do { _Pragma("unroll") for (int n = 0; n < 2; ++n) _Pragma("unroll") for (int k = 0; k < 2; ++k) dst[n][k] = *(const LAS bf16x8*)(lds + PG8_SB(b, h) + boff + n * 2048 + k * 1024); } while (0)
; #define PG8_MMA(ai, bj, At, Bt) do { __builtin_amdgcn_s_setprio(1); _Pragma("unroll") for (int m = 0; m < 4; ++m) _Pragma("unroll") for (int n = 0; n < 2; ++n) _Pragma("unroll") for (int k = 0; k < 2; ++k) \
;         acc[ai][bj][m][n] = __builtin_amdgcn_mfma_f32_16x16x32_bf16(Bt[n][k], At[m][k], acc[ai][bj][m][n], 0, 0, 0); __builtin_amdgcn_s_setprio(0); } while (0)
; #define PG8_WAIT_V(n) asm volatile("s_waitcnt vmcnt(" #n ")" ::: "memory")
; #define PG8_WAIT_L(n) asm volatile("s_waitcnt lgkmcnt(" #n ")" ::: "memory")
; #define PG8_BAR __builtin_amdgcn_s_barrier()
; #define PG8_SCHED __builtin_amdgcn_sched_barrier(0)
; template <class Epi, bool ALIGN_EPI>
; __device__ __forceinline__ void gemm_phase(LAS unsigned char* lds, const Gemm g, int G, int cid, const Epi& E) {
;     ...
;             PG8_LDB(B0, 0, 0); PG8_LDB(B1, 0, 1); PG8_SCHED; PG8_LDA(At, 0, 0); PG8_STAGE(PG8_SA(1, 1), a1 + hA, voffA);
;             PG8_WAIT_V(8); PG8_WAIT_L(0); PG8_BAR; PG8_MMA(0, 0, At, B0); PG8_MMA(0, 1, At, B1); PG8_BAR; PG8_SCHED;
;             PG8_LDA(At, 0, 1); PG8_STAGE(PG8_SB(0, 0), b2, voffB); PG8_STAGE(PG8_SB(0, 1), b2 + hB, voffB); PG8_STAGE(PG8_SA(0, 0), a2, voffA);
;             PG8_WAIT_V(8); PG8_WAIT_L(0); PG8_BAR; PG8_MMA(1, 0, At, B0); PG8_MMA(1, 1, At, B1); PG8_BAR; PG8_SCHED;
.LBB0_169:
	s_add_u32 s44, s50, 0x100
	s_addc_u32 s45, s51, 0
	s_add_i32 s6, 0, 0x10000
	s_cmp_eq_u32 s79, 4
	s_cselect_b32 s55, s43, s45
	s_cselect_b32 s54, s42, s44
	s_cselect_b32 s53, s30, s78
	s_cselect_b32 s52, s76, s77
	s_add_i32 s86, 0, 0x14000
	v_add_u32_e32 v84, s6, v212
	v_add_u32_e32 v100, s86, v212
	ds_read_b128 v[68:71], v84
	ds_read_b128 v[76:79], v84 offset:1024
	ds_read_b128 v[80:83], v84 offset:2048
	ds_read_b128 v[84:87], v84 offset:3072
	ds_read_b128 v[88:91], v100
	ds_read_b128 v[92:95], v100 offset:1024
	ds_read_b128 v[96:99], v100 offset:2048
	ds_read_b128 v[100:103], v100 offset:3072
	v_lshl_add_u64 v[198:199], s[50:51], 0, v[184:185]
	s_add_i32 m0, s24, 0xc000
	ds_read_b128 v[164:167], v214
	ds_read_b128 v[168:171], v214 offset:1024
	ds_read_b128 v[172:175], v214 offset:2048
	ds_read_b128 v[176:179], v214 offset:3072
	ds_read_b128 v[188:191], v214 offset:4096
	ds_read_b128 v[206:209], v214 offset:5120
	ds_read_b128 v[216:219], v214 offset:6144
	ds_read_b128 v[220:223], v214 offset:7168
	global_load_lds_dwordx4 v[198:199], off
	v_lshl_add_u64 v[198:199], s[50:51], 0, v[186:187]
	s_add_i32 m0, s24, 0xe000
	s_nop 0
	global_load_lds_dwordx4 v[198:199], off
	s_waitcnt vmcnt(8)
	s_waitcnt lgkmcnt(0)
	s_barrier
	s_waitcnt lgkmcnt(0)
	v_mfma_f32_16x16x32_bf16 v[160:163], v[68:71], v[164:167], v[160:163]
	v_mfma_f32_16x16x32_bf16 v[156:159], v[80:83], v[164:167], v[156:159]
	v_mfma_f32_16x16x32_bf16 v[144:147], v[68:71], v[172:175], v[144:147]
	v_mfma_f32_16x16x32_bf16 v[140:143], v[80:83], v[172:175], v[140:143]
	v_mfma_f32_16x16x32_bf16 v[124:127], v[68:71], v[188:191], v[124:127]
	v_mfma_f32_16x16x32_bf16 v[120:123], v[80:83], v[188:191], v[120:123]
	v_mfma_f32_16x16x32_bf16 v[108:111], v[68:71], v[216:219], v[108:111]
	v_mfma_f32_16x16x32_bf16 v[104:107], v[80:83], v[216:219], v[104:107]
	v_mfma_f32_16x16x32_bf16 v[160:163], v[76:79], v[168:171], v[160:163]
	v_mfma_f32_16x16x32_bf16 v[156:159], v[84:87], v[168:171], v[156:159]
	v_mfma_f32_16x16x32_bf16 v[144:147], v[76:79], v[176:179], v[144:147]
	v_mfma_f32_16x16x32_bf16 v[140:143], v[84:87], v[176:179], v[140:143]
	v_mfma_f32_16x16x32_bf16 v[124:127], v[76:79], v[206:209], v[124:127]
	v_mfma_f32_16x16x32_bf16 v[120:123], v[84:87], v[206:209], v[120:123]
	v_mfma_f32_16x16x32_bf16 v[108:111], v[76:79], v[220:223], v[108:111]
	v_mfma_f32_16x16x32_bf16 v[104:107], v[84:87], v[220:223], v[104:107]
	v_mfma_f32_16x16x32_bf16 v[152:155], v[88:91], v[164:167], v[152:155]
	v_mfma_f32_16x16x32_bf16 v[148:151], v[96:99], v[164:167], v[148:151]
	v_mfma_f32_16x16x32_bf16 v[132:135], v[88:91], v[172:175], v[132:135]
	v_mfma_f32_16x16x32_bf16 v[128:131], v[96:99], v[172:175], v[128:131]
	v_mfma_f32_16x16x32_bf16 v[116:119], v[88:91], v[188:191], v[116:119]
	v_mfma_f32_16x16x32_bf16 v[112:115], v[96:99], v[188:191], v[112:115]
	v_mfma_f32_16x16x32_bf16 v[72:75], v[88:91], v[216:219], v[72:75]
	v_mfma_f32_16x16x32_bf16 v[64:67], v[96:99], v[216:219], v[64:67]
	v_mfma_f32_16x16x32_bf16 v[152:155], v[92:95], v[168:171], v[152:155]
	v_mfma_f32_16x16x32_bf16 v[148:151], v[100:103], v[168:171], v[148:151]
	v_mfma_f32_16x16x32_bf16 v[132:135], v[92:95], v[176:179], v[132:135]
	v_mfma_f32_16x16x32_bf16 v[128:131], v[100:103], v[176:179], v[128:131]
	v_mfma_f32_16x16x32_bf16 v[116:119], v[92:95], v[206:209], v[116:119]
	v_mfma_f32_16x16x32_bf16 v[112:115], v[100:103], v[206:209], v[112:115]
	v_mfma_f32_16x16x32_bf16 v[72:75], v[92:95], v[220:223], v[72:75]
	v_mfma_f32_16x16x32_bf16 v[64:67], v[100:103], v[220:223], v[64:67]
	s_barrier
	s_add_i32 s6, s6, s23
	v_lshl_add_u64 v[198:199], s[52:53], 0, v[138:139]
	s_mov_b32 m0, s6
	ds_read_b128 v[164:167], v214 offset:16384
	ds_read_b128 v[168:171], v214 offset:17408
	ds_read_b128 v[172:175], v214 offset:18432
	ds_read_b128 v[176:179], v214 offset:19456
	ds_read_b128 v[188:191], v214 offset:20480
	ds_read_b128 v[206:209], v214 offset:21504
	ds_read_b128 v[216:219], v214 offset:22528
	ds_read_b128 v[220:223], v214 offset:23552
	global_load_lds_dwordx4 v[198:199], off
	s_add_i32 m0, s6, 0x2000
	s_add_u32 s6, s52, 0x2000
	v_lshl_add_u64 v[198:199], s[52:53], 0, v[136:137]
	s_addc_u32 s7, s53, 0
	s_add_i32 s50, s86, s23
	global_load_lds_dwordx4 v[198:199], off
	v_lshl_add_u64 v[198:199], s[6:7], 0, v[138:139]
	s_mov_b32 m0, s50
	v_lshl_add_u64 v[200:201], s[54:55], 0, v[180:181]
	global_load_lds_dwordx4 v[198:199], off
	v_lshl_add_u64 v[198:199], s[6:7], 0, v[136:137]
	s_add_i32 m0, s50, 0x2000
	s_nop 0
	global_load_lds_dwordx4 v[198:199], off
	v_lshl_add_u64 v[198:199], s[54:55], 0, v[182:183]
	s_mov_b32 m0, s24
	s_nop 0
	global_load_lds_dwordx4 v[198:199], off
	s_mov_b32 m0, s25
	s_nop 0
	global_load_lds_dwordx4 v[200:201], off
	s_waitcnt vmcnt(8)
	s_waitcnt lgkmcnt(0)
	s_barrier
; #define PG8_STAGE(bufoff, gbase, voff) do { _Pragma("unroll") for (int _i = 0; _i < 2; ++_i) \
;         __builtin_amdgcn_global_load_lds((const unsigned*)((const char*)(gbase) + (voff)[_i]), (LAS unsigned*)(lds + (bufoff) + ldsw + _i * 8192), 16, 0, 0); } while (0)
; #define PG8_LDA(dst, b, h) do { _Pragma("unroll") for (int m = 0; m < 4; ++m) _Pragma("unroll") for (int k = 0; k < 2; ++k) dst[m][k] = *(const LAS bf16x8*)(lds + PG8_SA(b, h) + aoff + m * 2048 + k * 1024); } while (0)
; #define PG8_LDB(dst, b, h) do { _Pragma("unroll") for (int n = 0; n < 2; ++n) _Pragma("unroll") for (int k = 0; k < 2; ++k) dst[n][k] = *(const LAS bf16x8*)(lds + PG8_SB(b, h) + boff + n * 2048 + k * 1024); } while (0)
; #define PG8_MMA(ai, bj, At, Bt) do { __builtin_amdgcn_s_setprio(1); _Pragma("unroll") for (int m = 0; m < 4; ++m) _Pragma("unroll") for (int n = 0; n < 2; ++n) _Pragma("unroll") for (int k = 0; k < 2; ++k) \
;         acc[ai][bj][m][n] = __builtin_amdgcn_mfma_f32_16x16x32_bf16(Bt[n][k], At[m][k], acc[ai][bj][m][n], 0, 0, 0); __builtin_amdgcn_s_setprio(0); } while (0)
; #define PG8_WAIT_V(n) asm volatile("s_waitcnt vmcnt(" #n ")" ::: "memory")
; #define PG8_WAIT_L(n) asm volatile("s_waitcnt lgkmcnt(" #n ")" ::: "memory")
; #define PG8_BAR __builtin_amdgcn_s_barrier()
; #define PG8_SCHED __builtin_amdgcn_sched_barrier(0)
; template <class Epi, bool ALIGN_EPI>
; __device__ __forceinline__ void gemm_phase(LAS unsigned char* lds, const Gemm g, int G, int cid, const Epi& E) {
;     ...
;             PG8_WAIT_V(8); PG8_WAIT_L(0); PG8_BAR; PG8_MMA(1, 0, At, B0); PG8_MMA(1, 1, At, B1); PG8_BAR; PG8_SCHED;
;             PG8_LDB(B0, 1, 0); PG8_LDB(B1, 1, 1); PG8_SCHED; PG8_LDA(At, 1, 0); PG8_STAGE(PG8_SA(0, 1), a2 + hA, voffA);
;             PG8_WAIT_V(8); PG8_WAIT_L(0); PG8_BAR; PG8_MMA(0, 0, At, B0); PG8_MMA(0, 1, At, B1); PG8_BAR; PG8_SCHED;
	s_waitcnt lgkmcnt(0)
	v_mfma_f32_16x16x32_bf16 v[60:63], v[68:71], v[164:167], v[60:63]
	v_mfma_f32_16x16x32_bf16 v[56:59], v[80:83], v[164:167], v[56:59]
	v_mfma_f32_16x16x32_bf16 v[44:47], v[68:71], v[172:175], v[44:47]
	v_mfma_f32_16x16x32_bf16 v[40:43], v[80:83], v[172:175], v[40:43]
	v_mfma_f32_16x16x32_bf16 v[28:31], v[68:71], v[188:191], v[28:31]
	v_mfma_f32_16x16x32_bf16 v[24:27], v[80:83], v[188:191], v[24:27]
	v_mfma_f32_16x16x32_bf16 v[12:15], v[68:71], v[216:219], v[12:15]
	v_mfma_f32_16x16x32_bf16 v[8:11], v[80:83], v[216:219], v[8:11]
	v_mfma_f32_16x16x32_bf16 v[60:63], v[76:79], v[168:171], v[60:63]
	v_mfma_f32_16x16x32_bf16 v[56:59], v[84:87], v[168:171], v[56:59]
	v_mfma_f32_16x16x32_bf16 v[44:47], v[76:79], v[176:179], v[44:47]
	v_mfma_f32_16x16x32_bf16 v[40:43], v[84:87], v[176:179], v[40:43]
	v_mfma_f32_16x16x32_bf16 v[28:31], v[76:79], v[206:209], v[28:31]
	v_mfma_f32_16x16x32_bf16 v[24:27], v[84:87], v[206:209], v[24:27]
	v_mfma_f32_16x16x32_bf16 v[12:15], v[76:79], v[220:223], v[12:15]
	v_mfma_f32_16x16x32_bf16 v[8:11], v[84:87], v[220:223], v[8:11]
	v_mfma_f32_16x16x32_bf16 v[52:55], v[88:91], v[164:167], v[52:55]
	v_mfma_f32_16x16x32_bf16 v[48:51], v[96:99], v[164:167], v[48:51]
	v_mfma_f32_16x16x32_bf16 v[36:39], v[88:91], v[172:175], v[36:39]
	v_mfma_f32_16x16x32_bf16 v[32:35], v[96:99], v[172:175], v[32:35]
	v_mfma_f32_16x16x32_bf16 v[20:23], v[88:91], v[188:191], v[20:23]
	v_mfma_f32_16x16x32_bf16 v[16:19], v[96:99], v[188:191], v[16:19]
	v_mfma_f32_16x16x32_bf16 v[4:7], v[88:91], v[216:219], v[4:7]
	v_mfma_f32_16x16x32_bf16 v[0:3], v[96:99], v[216:219], v[0:3]
	v_mfma_f32_16x16x32_bf16 v[52:55], v[92:95], v[168:171], v[52:55]
	v_mfma_f32_16x16x32_bf16 v[48:51], v[100:103], v[168:171], v[48:51]
	v_mfma_f32_16x16x32_bf16 v[36:39], v[92:95], v[176:179], v[36:39]
	v_mfma_f32_16x16x32_bf16 v[32:35], v[100:103], v[176:179], v[32:35]
	v_mfma_f32_16x16x32_bf16 v[20:23], v[92:95], v[206:209], v[20:23]
	v_mfma_f32_16x16x32_bf16 v[16:19], v[100:103], v[206:209], v[16:19]
	v_mfma_f32_16x16x32_bf16 v[4:7], v[92:95], v[220:223], v[4:7]
	v_mfma_f32_16x16x32_bf16 v[0:3], v[100:103], v[220:223], v[0:3]
	s_barrier
	s_add_i32 s50, 0, 0x18000
	s_add_i32 s51, 0, 0x1c000
	v_add_u32_e32 v84, s50, v212
	v_add_u32_e32 v100, s51, v212
	ds_read_b128 v[68:71], v84
	ds_read_b128 v[76:79], v84 offset:1024
	ds_read_b128 v[80:83], v84 offset:2048
	ds_read_b128 v[84:87], v84 offset:3072
	ds_read_b128 v[88:91], v100
	ds_read_b128 v[92:95], v100 offset:1024
	ds_read_b128 v[96:99], v100 offset:2048
	ds_read_b128 v[100:103], v100 offset:3072
	s_add_u32 s6, s54, 0x84000
	s_addc_u32 s7, s55, 0
	s_mov_b32 m0, s56
	v_lshl_add_u64 v[210:211], s[6:7], 0, v[182:183]
	ds_read_b128 v[164:167], v214 offset:32768
	ds_read_b128 v[168:171], v214 offset:33792
	ds_read_b128 v[172:175], v214 offset:34816
	ds_read_b128 v[176:179], v214 offset:35840
	ds_read_b128 v[188:191], v214 offset:36864
	ds_read_b128 v[206:209], v214 offset:37888
	ds_read_b128 v[216:219], v214 offset:38912
	ds_read_b128 v[220:223], v214 offset:39936
	global_load_lds_dwordx4 v[210:211], off
	v_lshl_add_u64 v[210:211], s[6:7], 0, v[180:181]
	s_mov_b32 m0, s57
	s_nop 0
	global_load_lds_dwordx4 v[210:211], off
	s_waitcnt vmcnt(8)
	s_waitcnt lgkmcnt(0)
	s_barrier
	s_waitcnt lgkmcnt(0)
	v_mfma_f32_16x16x32_bf16 v[160:163], v[68:71], v[164:167], v[160:163]
	v_mfma_f32_16x16x32_bf16 v[156:159], v[80:83], v[164:167], v[156:159]
	v_mfma_f32_16x16x32_bf16 v[144:147], v[68:71], v[172:175], v[144:147]
	v_mfma_f32_16x16x32_bf16 v[140:143], v[80:83], v[172:175], v[140:143]
	v_mfma_f32_16x16x32_bf16 v[124:127], v[68:71], v[188:191], v[124:127]
	v_mfma_f32_16x16x32_bf16 v[120:123], v[80:83], v[188:191], v[120:123]
	v_mfma_f32_16x16x32_bf16 v[108:111], v[68:71], v[216:219], v[108:111]
	v_mfma_f32_16x16x32_bf16 v[104:107], v[80:83], v[216:219], v[104:107]
	v_mfma_f32_16x16x32_bf16 v[160:163], v[76:79], v[168:171], v[160:163]
	v_mfma_f32_16x16x32_bf16 v[156:159], v[84:87], v[168:171], v[156:159]
	v_mfma_f32_16x16x32_bf16 v[144:147], v[76:79], v[176:179], v[144:147]
	v_mfma_f32_16x16x32_bf16 v[140:143], v[84:87], v[176:179], v[140:143]
	v_mfma_f32_16x16x32_bf16 v[124:127], v[76:79], v[206:209], v[124:127]
	v_mfma_f32_16x16x32_bf16 v[120:123], v[84:87], v[206:209], v[120:123]
	v_mfma_f32_16x16x32_bf16 v[108:111], v[76:79], v[220:223], v[108:111]
	v_mfma_f32_16x16x32_bf16 v[104:107], v[84:87], v[220:223], v[104:107]
	v_mfma_f32_16x16x32_bf16 v[152:155], v[88:91], v[164:167], v[152:155]
	v_mfma_f32_16x16x32_bf16 v[148:151], v[96:99], v[164:167], v[148:151]
	v_mfma_f32_16x16x32_bf16 v[132:135], v[88:91], v[172:175], v[132:135]
	v_mfma_f32_16x16x32_bf16 v[128:131], v[96:99], v[172:175], v[128:131]
	v_mfma_f32_16x16x32_bf16 v[116:119], v[88:91], v[188:191], v[116:119]
	v_mfma_f32_16x16x32_bf16 v[112:115], v[96:99], v[188:191], v[112:115]
	v_mfma_f32_16x16x32_bf16 v[72:75], v[88:91], v[216:219], v[72:75]
	v_mfma_f32_16x16x32_bf16 v[64:67], v[96:99], v[216:219], v[64:67]
	v_mfma_f32_16x16x32_bf16 v[152:155], v[92:95], v[168:171], v[152:155]
	v_mfma_f32_16x16x32_bf16 v[148:151], v[100:103], v[168:171], v[148:151]
	v_mfma_f32_16x16x32_bf16 v[132:135], v[92:95], v[176:179], v[132:135]
	v_mfma_f32_16x16x32_bf16 v[128:131], v[100:103], v[176:179], v[128:131]
	v_mfma_f32_16x16x32_bf16 v[116:119], v[92:95], v[206:209], v[116:119]
	v_mfma_f32_16x16x32_bf16 v[112:115], v[100:103], v[206:209], v[112:115]
	v_mfma_f32_16x16x32_bf16 v[72:75], v[92:95], v[220:223], v[72:75]
	v_mfma_f32_16x16x32_bf16 v[64:67], v[100:103], v[220:223], v[64:67]
	s_barrier
; #define PG8_STAGE(bufoff, gbase, voff) do { _Pragma("unroll") for (int _i = 0; _i < 2; ++_i) \
;         __builtin_amdgcn_global_load_lds((const unsigned*)((const char*)(gbase) + (voff)[_i]), (LAS unsigned*)(lds + (bufoff) + ldsw + _i * 8192), 16, 0, 0); } while (0)
; #define PG8_LDA(dst, b, h) do { _Pragma("unroll") for (int m = 0; m < 4; ++m) _Pragma("unroll") for (int k = 0; k < 2; ++k) dst[m][k] = *(const LAS bf16x8*)(lds + PG8_SA(b, h) + aoff + m * 2048 + k * 1024); } while (0)
; #define PG8_MMA(ai, bj, At, Bt) do { __builtin_amdgcn_s_setprio(1); _Pragma("unroll") for (int m = 0; m < 4; ++m) _Pragma("unroll") for (int n = 0; n < 2; ++n) _Pragma("unroll") for (int k = 0; k < 2; ++k) \
;         acc[ai][bj][m][n] = __builtin_amdgcn_mfma_f32_16x16x32_bf16(Bt[n][k], At[m][k], acc[ai][bj][m][n], 0, 0, 0); __builtin_amdgcn_s_setprio(0); } while (0)
; #define PG8_WAIT_V(n) asm volatile("s_waitcnt vmcnt(" #n ")" ::: "memory")
; #define PG8_WAIT_L(n) asm volatile("s_waitcnt lgkmcnt(" #n ")" ::: "memory")
; #define PG8_BAR __builtin_amdgcn_s_barrier()
; #define PG8_SCHED __builtin_amdgcn_sched_barrier(0)
; template <class Epi, bool ALIGN_EPI>
; __device__ __forceinline__ void gemm_phase(LAS unsigned char* lds, const Gemm g, int G, int cid, const Epi& E) {
;     ...
;             PG8_LDA(At, 1, 1); PG8_STAGE(PG8_SB(1, 0), b3, voffB); PG8_STAGE(PG8_SB(1, 1), b3 + hB, voffB); PG8_STAGE(PG8_SA(1, 0), a3, voffA);
;             PG8_WAIT_V(8); PG8_WAIT_L(0); PG8_BAR; PG8_MMA(1, 0, At, B0); PG8_MMA(1, 1, At, B1); PG8_BAR; PG8_SCHED;
	s_add_u32 s6, s52, 0x10000
	s_addc_u32 s7, s53, 0
	s_add_i32 s50, s50, s23
	v_lshl_add_u64 v[210:211], s[6:7], 0, v[138:139]
	s_mov_b32 m0, s50
	ds_read_b128 v[164:167], v214 offset:49152
	ds_read_b128 v[168:171], v214 offset:50176
	ds_read_b128 v[172:175], v214 offset:51200
	ds_read_b128 v[176:179], v214 offset:52224
	ds_read_b128 v[188:191], v214 offset:53248
	ds_read_b128 v[206:209], v214 offset:54272
	ds_read_b128 v[216:219], v214 offset:55296
	ds_read_b128 v[220:223], v214 offset:56320
	global_load_lds_dwordx4 v[210:211], off
	s_add_i32 m0, s50, 0x2000
	v_lshl_add_u64 v[210:211], s[6:7], 0, v[136:137]
	s_add_u32 s6, s52, 0x12000
	s_addc_u32 s7, s53, 0
	s_add_i32 s50, s51, s23
	global_load_lds_dwordx4 v[210:211], off
	v_lshl_add_u64 v[210:211], s[6:7], 0, v[138:139]
	s_mov_b32 m0, s50
	v_lshl_add_u64 v[198:199], v[198:199], 0, s[36:37]
	global_load_lds_dwordx4 v[210:211], off
	v_lshl_add_u64 v[210:211], s[6:7], 0, v[136:137]
	s_add_i32 m0, s50, 0x2000
	s_nop 0
	global_load_lds_dwordx4 v[210:211], off
	s_mov_b32 m0, s59
	s_nop 0
	global_load_lds_dwordx4 v[198:199], off
	v_lshl_add_u64 v[198:199], v[200:201], 0, s[36:37]
	s_mov_b32 m0, s72
	s_nop 0
	global_load_lds_dwordx4 v[198:199], off
	s_waitcnt vmcnt(8)
	s_waitcnt lgkmcnt(0)
	s_barrier
	s_waitcnt lgkmcnt(0)
	v_mfma_f32_16x16x32_bf16 v[60:63], v[68:71], v[164:167], v[60:63]
	v_mfma_f32_16x16x32_bf16 v[56:59], v[80:83], v[164:167], v[56:59]
	v_mfma_f32_16x16x32_bf16 v[44:47], v[68:71], v[172:175], v[44:47]
	v_mfma_f32_16x16x32_bf16 v[40:43], v[80:83], v[172:175], v[40:43]
	v_mfma_f32_16x16x32_bf16 v[28:31], v[68:71], v[188:191], v[28:31]
	v_mfma_f32_16x16x32_bf16 v[24:27], v[80:83], v[188:191], v[24:27]
	v_mfma_f32_16x16x32_bf16 v[12:15], v[68:71], v[216:219], v[12:15]
	v_mfma_f32_16x16x32_bf16 v[8:11], v[80:83], v[216:219], v[8:11]
	v_mfma_f32_16x16x32_bf16 v[60:63], v[76:79], v[168:171], v[60:63]
	v_mfma_f32_16x16x32_bf16 v[56:59], v[84:87], v[168:171], v[56:59]
	v_mfma_f32_16x16x32_bf16 v[44:47], v[76:79], v[176:179], v[44:47]
	v_mfma_f32_16x16x32_bf16 v[40:43], v[84:87], v[176:179], v[40:43]
	v_mfma_f32_16x16x32_bf16 v[28:31], v[76:79], v[206:209], v[28:31]
	v_mfma_f32_16x16x32_bf16 v[24:27], v[84:87], v[206:209], v[24:27]
	v_mfma_f32_16x16x32_bf16 v[12:15], v[76:79], v[220:223], v[12:15]
	v_mfma_f32_16x16x32_bf16 v[8:11], v[84:87], v[220:223], v[8:11]
	v_mfma_f32_16x16x32_bf16 v[52:55], v[88:91], v[164:167], v[52:55]
	v_mfma_f32_16x16x32_bf16 v[48:51], v[96:99], v[164:167], v[48:51]
	v_mfma_f32_16x16x32_bf16 v[36:39], v[88:91], v[172:175], v[36:39]
	v_mfma_f32_16x16x32_bf16 v[32:35], v[96:99], v[172:175], v[32:35]
	v_mfma_f32_16x16x32_bf16 v[20:23], v[88:91], v[188:191], v[20:23]
	v_mfma_f32_16x16x32_bf16 v[16:19], v[96:99], v[188:191], v[16:19]
	v_mfma_f32_16x16x32_bf16 v[4:7], v[88:91], v[216:219], v[4:7]
	v_mfma_f32_16x16x32_bf16 v[0:3], v[96:99], v[216:219], v[0:3]
	v_mfma_f32_16x16x32_bf16 v[52:55], v[92:95], v[168:171], v[52:55]
	v_mfma_f32_16x16x32_bf16 v[48:51], v[100:103], v[168:171], v[48:51]
	v_mfma_f32_16x16x32_bf16 v[36:39], v[92:95], v[176:179], v[36:39]
	v_mfma_f32_16x16x32_bf16 v[32:35], v[100:103], v[176:179], v[32:35]
	v_mfma_f32_16x16x32_bf16 v[20:23], v[92:95], v[206:209], v[20:23]
	v_mfma_f32_16x16x32_bf16 v[16:19], v[100:103], v[206:209], v[16:19]
	v_mfma_f32_16x16x32_bf16 v[4:7], v[92:95], v[220:223], v[4:7]
	v_mfma_f32_16x16x32_bf16 v[0:3], v[100:103], v[220:223], v[0:3]
	s_barrier
	s_add_i32 s79, s79, 2
	s_add_u32 s77, s77, 0x20000
	s_addc_u32 s78, s78, 0
	s_cmp_lt_u32 s79, 6
	s_mov_b64 s[50:51], s[44:45]
	s_cbranch_scc1 .LBB0_169
; __device__ __forceinline__ unsigned cvt_pk_bf16(float lo, float hi) { unsigned r; asm volatile("v_cvt_pk_bf16_f32 %0, %1, %2" : "=v"(r) : "v"(lo), "v"(hi)); return r; }
;     __device__ __forceinline__ void operator()(const f32x4 (&acc)[2][2][4][2], const Unit& u, int wr, int wc, int fr, int fq, const LAS float*) const {
;     ...
;             for (int n = 0; n < 2; ++n) { bv[bj][n] = HB ? *(const f32x4*)(bias + col0 + bj * HALF + 4 * n) : (f32x4){0.f, 0.f, 0.f, 0.f};
;                                            sv[bj][n] = HB ? *(const f32x4*)(scale + col0 + bj * HALF + 4 * n) : (f32x4){1.f, 1.f, 1.f, 1.f}; }
;         constexpr int NB = HB ? 4 : 2, MB = 4 / (NB / 2);
; #pragma unroll
;         for (int am = 0; am < NB; ++am) { const int ai = am / (NB / 2), m0 = (am % (NB / 2)) * MB;
;             f32x4 xo[4][2][2];
; #pragma unroll
;             for (int m = m0; m < m0 + MB; ++m) { const float* xr = Xs + (size_t)(row0 + ai * HALF + m * 16) * DM + col0;
; #pragma unroll
;                 for (int bj = 0; bj < 2; ++bj) { xo[m][bj][0] = *(const f32x4*)(xr + bj * HALF); xo[m][bj][1] = *(const f32x4*)(xr + bj * HALF + 4); } }
; #pragma unroll
;             for (int m = m0; m < m0 + MB; ++m) { const int row = row0 + ai * HALF + m * 16; float ss = 0.f;
;                 float* xr = X + (size_t)row * DM + col0; bf16_t* xb = XB + (size_t)row * ALD + col0;
; #pragma unroll
;                 for (int bj = 0; bj < 2; ++bj) { f32x4 x0 = xo[m][bj][0], x1 = xo[m][bj][1];
;                     if (HB) { x0 += (acc[ai][bj][m][0] + bv[bj][0]) * sv[bj][0]; x1 += (acc[ai][bj][m][1] + bv[bj][1]) * sv[bj][1]; } else { x0 += acc[ai][bj][m][0]; x1 += acc[ai][bj][m][1]; }
;                     *(f32x4*)(xr + bj * HALF) = x0; *(f32x4*)(xr + bj * HALF + 4) = x1;
;                     ss += (x0[0] * x0[0] + x0[1] * x0[1]) + (x0[2] * x0[2] + x0[3] * x0[3]) + (x1[0] * x1[0] + x1[1] * x1[1]) + (x1[2] * x1[2] + x1[3] * x1[3]);
;                     u32x4 w; w.x = cvt_pk_bf16(x0[0], x0[1]); w.y = cvt_pk_bf16(x0[2], x0[3]); w.z = cvt_pk_bf16(x1[0], x1[1]); w.w = cvt_pk_bf16(x1[2], x1[3]);
;                     if (feeds) *(u32x4*)(xb + bj * HALF) = w; }
;                 ss += __shfl_xor(ss, 16); ss += __shfl_xor(ss, 32);
;                 if (fq == 0 && feeds) part[(size_t)row * NPART + u.pn * 4 + wc] = ss; }
	v_lshl_or_b32 v188, s12, 8, v213
	v_ashrrev_i32_e32 v189, 31, v188
	v_lshl_add_u32 v190, s13, 8, v197
	v_lshlrev_b64 v[198:199], 2, v[188:189]
	v_ashrrev_i32_e32 v191, 31, v190
	v_lshl_add_u64 v[206:207], s[82:83], 0, v[198:199]
	v_lshlrev_b64 v[200:201], 13, v[190:191]
	v_lshl_add_u64 v[68:69], s[28:29], 0, v[198:199]
	v_lshl_add_u64 v[80:81], s[46:47], 0, v[198:199]
	v_lshl_add_u64 v[164:165], v[206:207], 0, v[200:201]
	global_load_dwordx4 v[92:95], v[68:69], off offset:16
	global_load_dwordx4 v[100:103], v[68:69], off
	global_load_dwordx4 v[88:91], v[80:81], off offset:16
	global_load_dwordx4 v[96:99], v[80:81], off
	global_load_dwordx4 v[76:79], v[68:69], off offset:528
	global_load_dwordx4 v[84:87], v[68:69], off offset:512
	s_nop 0
	global_load_dwordx4 v[68:71], v[80:81], off offset:528
	s_nop 0
	global_load_dwordx4 v[80:83], v[80:81], off offset:512
	s_nop 0
	global_load_dwordx4 v[216:219], v[164:165], off offset:16
	global_load_dwordx4 v[220:223], v[164:165], off
	global_load_dwordx4 v[224:227], v[164:165], off offset:528
	global_load_dwordx4 v[228:231], v[164:165], off offset:512
	v_or_b32_e32 v208, 16, v190
	v_ashrrev_i32_e32 v209, 31, v208
	v_lshlrev_b64 v[210:211], 13, v[208:209]
	v_lshl_add_u64 v[168:169], v[206:207], 0, v[210:211]
	global_load_dwordx4 v[172:175], v[168:169], off offset:16
	global_load_dwordx4 v[176:179], v[168:169], off
	global_load_dwordx4 v[164:167], v[168:169], off offset:528
	s_nop 0
	global_load_dwordx4 v[168:171], v[168:169], off offset:512
	v_lshl_add_u64 v[200:201], s[82:83], 0, v[200:201]
	v_lshl_add_u64 v[198:199], v[200:201], 0, v[198:199]
	v_mov_b64_e32 v[200:201], s[4:5]
	v_mad_i64_i32 v[200:201], s[6:7], v190, s66, v[200:201]
	v_lshl_add_u64 v[200:201], v[188:189], 1, v[200:201]
	s_lshl_b32 s44, s12, 2
	s_ashr_i32 s45, s44, 31
	s_waitcnt vmcnt(0)
	v_pk_add_f32 v[156:157], v[156:157], v[92:93]
	v_pk_add_f32 v[162:163], v[162:163], v[102:103]
	v_pk_add_f32 v[160:161], v[160:161], v[100:101]
	v_pk_add_f32 v[158:159], v[158:159], v[94:95]
	v_pk_add_f32 v[148:149], v[148:149], v[76:77]
	v_pk_fma_f32 v[156:157], v[88:89], v[156:157], v[216:217]
	v_pk_fma_f32 v[162:163], v[98:99], v[162:163], v[222:223]
	v_pk_fma_f32 v[160:161], v[96:97], v[160:161], v[220:221]
	v_mul_f32_e32 v216, v163, v163
	v_mul_f32_e32 v215, v161, v161
	v_fmac_f32_e32 v215, v160, v160
	v_fmac_f32_e32 v216, v162, v162
	v_pk_add_f32 v[154:155], v[154:155], v[86:87]
	v_pk_add_f32 v[152:153], v[152:153], v[84:85]
	v_add_f32_e32 v215, v215, v216
	v_mul_f32_e32 v216, v157, v157
	v_pk_fma_f32 v[154:155], v[82:83], v[154:155], v[230:231]
	v_pk_fma_f32 v[152:153], v[80:81], v[152:153], v[228:229]
	v_pk_fma_f32 v[158:159], v[90:91], v[158:159], v[218:219]
	global_store_dwordx4 v[198:199], v[160:163], off
	global_store_dwordx4 v[198:199], v[156:159], off offset:16
	v_fmac_f32_e32 v216, v156, v156
	v_cvt_pk_bf16_f32 v160, v160, v161
	v_cvt_pk_bf16_f32 v161, v162, v163
	v_cvt_pk_bf16_f32 v162, v156, v157
	v_pk_fma_f32 v[148:149], v[68:69], v[148:149], v[224:225]
	v_mul_f32_e32 v156, v153, v153
	v_mul_f32_e32 v157, v155, v155
	v_fmac_f32_e32 v156, v152, v152
	v_fmac_f32_e32 v157, v154, v154
	v_pk_add_f32 v[150:151], v[150:151], v[78:79]
	v_add_f32_e32 v156, v156, v157
	v_mul_f32_e32 v157, v149, v149
	v_cvt_pk_bf16_f32 v163, v158, v159
	global_store_dwordx4 v[200:201], v[160:163], off
	v_pk_fma_f32 v[150:151], v[70:71], v[150:151], v[226:227]
	global_store_dwordx4 v[198:199], v[152:155], off offset:512
	global_store_dwordx4 v[198:199], v[148:151], off offset:528
	v_fmac_f32_e32 v157, v148, v148
	v_cvt_pk_bf16_f32 v152, v152, v153
	v_cvt_pk_bf16_f32 v153, v154, v155
	v_cvt_pk_bf16_f32 v154, v148, v149
	v_add_f32_e32 v215, v215, v216
	v_and_b32_e32 v149, 64, v239
	v_mul_f32_e32 v216, v159, v159
	v_add_f32_e32 v156, v156, v157
	v_mul_f32_e32 v157, v151, v151
	v_xor_b32_e32 v148, 16, v239
	v_add_u32_e32 v149, 64, v149
	v_fmac_f32_e32 v216, v158, v158
	v_fmac_f32_e32 v157, v150, v150
	v_cmp_lt_i32_e32 vcc, v148, v149
	v_add_f32_e32 v215, v216, v215
	v_add_f32_e32 v156, v157, v156
	v_cndmask_b32_e32 v148, v239, v148, vcc
	v_add_f32_e32 v156, v215, v156
	v_cvt_pk_bf16_f32 v155, v150, v151
	global_store_dwordx4 v[200:201], v[152:155], off offset:256
	v_xor_b32_e32 v150, 32, v239
	v_cmp_lt_i32_e32 vcc, v150, v149
	v_lshlrev_b32_e32 v154, 2, v148
	ds_bpermute_b32 v148, v154, v156
	v_cndmask_b32_e32 v149, v239, v150, vcc
	v_lshlrev_b32_e32 v155, 2, v149
	s_waitcnt lgkmcnt(0)
	v_add_f32_e32 v148, v156, v148
	ds_bpermute_b32 v149, v155, v148
	s_and_saveexec_b64 s[50:51], s[38:39]
	s_cbranch_execz .LBB0_172
	v_lshlrev_b64 v[150:151], 7, v[190:191]
	v_lshl_add_u64 v[150:151], s[94:95], 0, v[150:151]
	v_lshl_add_u64 v[150:151], s[44:45], 2, v[150:151]
	s_lshl_b32 s30, s58, 2
	v_lshl_add_u64 v[150:151], v[150:151], 0, s[30:31]
	s_waitcnt lgkmcnt(0)
	v_add_f32_e32 v148, v148, v149
	global_store_dword v[150:151], v148, off

; #define PG8_STAGE(bufoff, gbase, voff) do { _Pragma("unroll") for (int _i = 0; _i < 2; ++_i) \
;         __builtin_amdgcn_global_load_lds((const unsigned*)((const char*)(gbase) + (voff)[_i]), (LAS unsigned*)(lds + (bufoff) + ldsw + _i * 8192), 16, 0, 0); } while (0)
; #define PG8_LDA(dst, b, h) do { _Pragma("unroll") for (int m = 0; m < 4; ++m) _Pragma("unroll") for (int k = 0; k < 2; ++k) dst[m][k] = *(const LAS bf16x8*)(lds + PG8_SA(b, h) + aoff + m * 2048 + k * 1024); } while (0)
; #define PG8_LDB(dst, b, h) do { _Pragma("unroll") for (int n = 0; n < 2; ++n) _Pragma("unroll") for (int k = 0; k < 2; ++k) dst[n][k] = *(const LAS bf16x8*)(lds + PG8_SB(b, h) + boff + n * 2048 + k * 1024); } while (0)
; #define PG8_MMA(ai, bj, At, Bt) do { __builtin_amdgcn_s_setprio(1); _Pragma("unroll") for (int m = 0; m < 4; ++m) _Pragma("unroll") for (int n = 0; n < 2; ++n) _Pragma("unroll") for (int k = 0; k < 2; ++k) \
;         acc[ai][bj][m][n] = __builtin_amdgcn_mfma_f32_16x16x32_bf16(Bt[n][k], At[m][k], acc[ai][bj][m][n], 0, 0, 0); __builtin_amdgcn_s_setprio(0); } while (0)
; #define PG8_WAIT_V(n) asm volatile("s_waitcnt vmcnt(" #n ")" ::: "memory")
; #define PG8_WAIT_L(n) asm volatile("s_waitcnt lgkmcnt(" #n ")" ::: "memory")
; #define PG8_BAR __builtin_amdgcn_s_barrier()
; #define PG8_SCHED __builtin_amdgcn_sched_barrier(0)
; template <class Epi, bool ALIGN_EPI>
; __device__ __forceinline__ void gemm_phase(LAS unsigned char* lds, const Gemm g, int G, int cid, const Epi& E) {
;     ...
;             const char* a1 = cA + (size_t)(t + 1) * kA;
;             const char* a2 = last ? nA : cA + (size_t)(t + 2) * kA; const char* b2 = last ? nB : cB + (size_t)(t + 2) * kB;
;             const char* a3 = a2 + kA; const char* b3 = b2 + kB;
;             PG8_LDB(B0, 0, 0); PG8_LDB(B1, 0, 1); PG8_SCHED; PG8_LDA(At, 0, 0); PG8_STAGE(PG8_SA(1, 1), a1 + hA, voffA);
;             PG8_WAIT_V(8); PG8_WAIT_L(0); PG8_BAR; PG8_MMA(0, 0, At, B0); PG8_MMA(0, 1, At, B1); PG8_BAR; PG8_SCHED;
;             PG8_LDA(At, 0, 1); PG8_STAGE(PG8_SB(0, 0), b2, voffB); PG8_STAGE(PG8_SB(0, 1), b2 + hB, voffB); PG8_STAGE(PG8_SA(0, 0), a2, voffA);
;             PG8_WAIT_V(8); PG8_WAIT_L(0); PG8_BAR; PG8_MMA(1, 0, At, B0); PG8_MMA(1, 1, At, B1); PG8_BAR; PG8_SCHED;
.LBB0_266:
	s_add_u32 s74, s72, 0x100
	s_addc_u32 s75, s73, 0
	s_and_b64 s[58:59], exec, s[58:59]
	s_cselect_b32 s59, s49, s75
	s_cselect_b32 s58, s48, s74
	s_add_i32 s6, 0, 0x10000
	s_add_i32 s7, 0, 0x14000
	v_add_u32_e32 v108, s6, v190
	v_add_u32_e32 v132, s7, v190
	ds_read_b128 v[88:91], v108
	ds_read_b128 v[100:103], v108 offset:1024
	ds_read_b128 v[104:107], v108 offset:2048
	ds_read_b128 v[108:111], v108 offset:3072
	ds_read_b128 v[112:115], v132
	ds_read_b128 v[120:123], v132 offset:1024
	ds_read_b128 v[124:127], v132 offset:2048
	ds_read_b128 v[132:135], v132 offset:3072
	v_lshl_add_u64 v[198:199], s[72:73], 0, v[178:179]
	s_add_i32 m0, s23, 0xc000
	ds_read_b128 v[164:167], v222
	ds_read_b128 v[168:171], v222 offset:1024
	ds_read_b128 v[182:185], v222 offset:2048
	ds_read_b128 v[224:227], v222 offset:3072
	ds_read_b128 v[228:231], v222 offset:4096
	ds_read_b128 v[232:235], v222 offset:5120
	ds_read_b128 v[244:247], v222 offset:6144
	ds_read_b128 v[248:251], v222 offset:7168
	global_load_lds_dwordx4 v[198:199], off
	v_lshl_add_u64 v[198:199], s[72:73], 0, v[180:181]
	s_add_i32 m0, s23, 0xe000
	s_nop 0
	global_load_lds_dwordx4 v[198:199], off
	s_waitcnt vmcnt(8)
	s_waitcnt lgkmcnt(0)
	s_barrier
	s_waitcnt lgkmcnt(0)
	v_mfma_f32_16x16x32_bf16 v[160:163], v[88:91], v[164:167], v[160:163]
	v_mfma_f32_16x16x32_bf16 v[156:159], v[104:107], v[164:167], v[156:159]
	v_mfma_f32_16x16x32_bf16 v[144:147], v[88:91], v[182:185], v[144:147]
	v_mfma_f32_16x16x32_bf16 v[140:143], v[104:107], v[182:185], v[140:143]
	v_mfma_f32_16x16x32_bf16 v[96:99], v[88:91], v[228:231], v[96:99]
	v_mfma_f32_16x16x32_bf16 v[92:95], v[104:107], v[228:231], v[92:95]
	v_mfma_f32_16x16x32_bf16 v[76:79], v[88:91], v[244:247], v[76:79]
	v_mfma_f32_16x16x32_bf16 v[72:75], v[104:107], v[244:247], v[72:75]
	v_mfma_f32_16x16x32_bf16 v[160:163], v[100:103], v[168:171], v[160:163]
	v_mfma_f32_16x16x32_bf16 v[156:159], v[108:111], v[168:171], v[156:159]
	v_mfma_f32_16x16x32_bf16 v[144:147], v[100:103], v[224:227], v[144:147]
	v_mfma_f32_16x16x32_bf16 v[140:143], v[108:111], v[224:227], v[140:143]
	v_mfma_f32_16x16x32_bf16 v[96:99], v[100:103], v[232:235], v[96:99]
	v_mfma_f32_16x16x32_bf16 v[92:95], v[108:111], v[232:235], v[92:95]
	v_mfma_f32_16x16x32_bf16 v[76:79], v[100:103], v[248:251], v[76:79]
	v_mfma_f32_16x16x32_bf16 v[72:75], v[108:111], v[248:251], v[72:75]
	v_mfma_f32_16x16x32_bf16 v[152:155], v[112:115], v[164:167], v[152:155]
	v_mfma_f32_16x16x32_bf16 v[148:151], v[124:127], v[164:167], v[148:151]
	v_mfma_f32_16x16x32_bf16 v[128:131], v[112:115], v[182:185], v[128:131]
	v_mfma_f32_16x16x32_bf16 v[116:119], v[124:127], v[182:185], v[116:119]
	v_mfma_f32_16x16x32_bf16 v[84:87], v[112:115], v[228:231], v[84:87]
	v_mfma_f32_16x16x32_bf16 v[80:83], v[124:127], v[228:231], v[80:83]
	v_mfma_f32_16x16x32_bf16 v[68:71], v[112:115], v[244:247], v[68:71]
	v_mfma_f32_16x16x32_bf16 v[64:67], v[124:127], v[244:247], v[64:67]
	v_mfma_f32_16x16x32_bf16 v[152:155], v[120:123], v[168:171], v[152:155]
	v_mfma_f32_16x16x32_bf16 v[148:151], v[132:135], v[168:171], v[148:151]
	v_mfma_f32_16x16x32_bf16 v[128:131], v[120:123], v[224:227], v[128:131]
	v_mfma_f32_16x16x32_bf16 v[116:119], v[132:135], v[224:227], v[116:119]
	v_mfma_f32_16x16x32_bf16 v[84:87], v[120:123], v[232:235], v[84:87]
	v_mfma_f32_16x16x32_bf16 v[80:83], v[132:135], v[232:235], v[80:83]
	v_mfma_f32_16x16x32_bf16 v[68:71], v[120:123], v[248:251], v[68:71]
	v_mfma_f32_16x16x32_bf16 v[64:67], v[132:135], v[248:251], v[64:67]
	s_barrier
	s_add_i32 s6, s6, s0
	v_lshl_add_u64 v[198:199], s[56:57], 0, v[172:173]
	s_mov_b32 m0, s6
	ds_read_b128 v[164:167], v222 offset:16384
	ds_read_b128 v[168:171], v222 offset:17408
	ds_read_b128 v[182:185], v222 offset:18432
	ds_read_b128 v[224:227], v222 offset:19456
	ds_read_b128 v[228:231], v222 offset:20480
	ds_read_b128 v[232:235], v222 offset:21504
	ds_read_b128 v[244:247], v222 offset:22528
	ds_read_b128 v[248:251], v222 offset:23552
	global_load_lds_dwordx4 v[198:199], off
	s_add_i32 m0, s6, 0x2000
	s_add_u32 s72, s56, 0x2000
	v_lshl_add_u64 v[198:199], s[56:57], 0, v[176:177]
	s_addc_u32 s73, s57, 0
	s_add_i32 s6, s7, s0
	global_load_lds_dwordx4 v[198:199], off
	v_lshl_add_u64 v[198:199], s[72:73], 0, v[172:173]
	s_mov_b32 m0, s6
	v_lshl_add_u64 v[200:201], s[58:59], 0, v[174:175]
	global_load_lds_dwordx4 v[198:199], off
	v_lshl_add_u64 v[198:199], s[72:73], 0, v[176:177]
	s_add_i32 m0, s6, 0x2000
	s_nop 0
	global_load_lds_dwordx4 v[198:199], off
	v_lshl_add_u64 v[198:199], s[58:59], 0, v[136:137]
	s_mov_b32 m0, s23
	s_nop 0
	global_load_lds_dwordx4 v[198:199], off
	s_mov_b32 m0, s24
	s_nop 0
	global_load_lds_dwordx4 v[200:201], off
	s_waitcnt vmcnt(8)
	s_waitcnt lgkmcnt(0)
	s_barrier
; #define PG8_STAGE(bufoff, gbase, voff) do { _Pragma("unroll") for (int _i = 0; _i < 2; ++_i) \
;         __builtin_amdgcn_global_load_lds((const unsigned*)((const char*)(gbase) + (voff)[_i]), (LAS unsigned*)(lds + (bufoff) + ldsw + _i * 8192), 16, 0, 0); } while (0)
; #define PG8_LDA(dst, b, h) do { _Pragma("unroll") for (int m = 0; m < 4; ++m) _Pragma("unroll") for (int k = 0; k < 2; ++k) dst[m][k] = *(const LAS bf16x8*)(lds + PG8_SA(b, h) + aoff + m * 2048 + k * 1024); } while (0)
; #define PG8_LDB(dst, b, h) do { _Pragma("unroll") for (int n = 0; n < 2; ++n) _Pragma("unroll") for (int k = 0; k < 2; ++k) dst[n][k] = *(const LAS bf16x8*)(lds + PG8_SB(b, h) + boff + n * 2048 + k * 1024); } while (0)
; #define PG8_MMA(ai, bj, At, Bt) do { __builtin_amdgcn_s_setprio(1); _Pragma("unroll") for (int m = 0; m < 4; ++m) _Pragma("unroll") for (int n = 0; n < 2; ++n) _Pragma("unroll") for (int k = 0; k < 2; ++k) \
;         acc[ai][bj][m][n] = __builtin_amdgcn_mfma_f32_16x16x32_bf16(Bt[n][k], At[m][k], acc[ai][bj][m][n], 0, 0, 0); __builtin_amdgcn_s_setprio(0); } while (0)
; #define PG8_WAIT_V(n) asm volatile("s_waitcnt vmcnt(" #n ")" ::: "memory")
; #define PG8_WAIT_L(n) asm volatile("s_waitcnt lgkmcnt(" #n ")" ::: "memory")
; #define PG8_BAR __builtin_amdgcn_s_barrier()
; #define PG8_SCHED __builtin_amdgcn_sched_barrier(0)
; template <class Epi, bool ALIGN_EPI>
; __device__ __forceinline__ void gemm_phase(LAS unsigned char* lds, const Gemm g, int G, int cid, const Epi& E) {
;     ...
;             PG8_WAIT_V(8); PG8_WAIT_L(0); PG8_BAR; PG8_MMA(1, 0, At, B0); PG8_MMA(1, 1, At, B1); PG8_BAR; PG8_SCHED;
;             PG8_LDB(B0, 1, 0); PG8_LDB(B1, 1, 1); PG8_SCHED; PG8_LDA(At, 1, 0); PG8_STAGE(PG8_SA(0, 1), a2 + hA, voffA);
;             PG8_WAIT_V(8); PG8_WAIT_L(0); PG8_BAR; PG8_MMA(0, 0, At, B0); PG8_MMA(0, 1, At, B1); PG8_BAR; PG8_SCHED;
	s_waitcnt lgkmcnt(0)
	v_mfma_f32_16x16x32_bf16 v[60:63], v[88:91], v[164:167], v[60:63]
	v_mfma_f32_16x16x32_bf16 v[56:59], v[104:107], v[164:167], v[56:59]
	v_mfma_f32_16x16x32_bf16 v[44:47], v[88:91], v[182:185], v[44:47]
	v_mfma_f32_16x16x32_bf16 v[40:43], v[104:107], v[182:185], v[40:43]
	v_mfma_f32_16x16x32_bf16 v[28:31], v[88:91], v[228:231], v[28:31]
	v_mfma_f32_16x16x32_bf16 v[24:27], v[104:107], v[228:231], v[24:27]
	v_mfma_f32_16x16x32_bf16 v[12:15], v[88:91], v[244:247], v[12:15]
	v_mfma_f32_16x16x32_bf16 v[8:11], v[104:107], v[244:247], v[8:11]
	v_mfma_f32_16x16x32_bf16 v[60:63], v[100:103], v[168:171], v[60:63]
	v_mfma_f32_16x16x32_bf16 v[56:59], v[108:111], v[168:171], v[56:59]
	v_mfma_f32_16x16x32_bf16 v[44:47], v[100:103], v[224:227], v[44:47]
	v_mfma_f32_16x16x32_bf16 v[40:43], v[108:111], v[224:227], v[40:43]
	v_mfma_f32_16x16x32_bf16 v[28:31], v[100:103], v[232:235], v[28:31]
	v_mfma_f32_16x16x32_bf16 v[24:27], v[108:111], v[232:235], v[24:27]
	v_mfma_f32_16x16x32_bf16 v[12:15], v[100:103], v[248:251], v[12:15]
	v_mfma_f32_16x16x32_bf16 v[8:11], v[108:111], v[248:251], v[8:11]
	v_mfma_f32_16x16x32_bf16 v[52:55], v[112:115], v[164:167], v[52:55]
	v_mfma_f32_16x16x32_bf16 v[48:51], v[124:127], v[164:167], v[48:51]
	v_mfma_f32_16x16x32_bf16 v[36:39], v[112:115], v[182:185], v[36:39]
	v_mfma_f32_16x16x32_bf16 v[32:35], v[124:127], v[182:185], v[32:35]
	v_mfma_f32_16x16x32_bf16 v[20:23], v[112:115], v[228:231], v[20:23]
	v_mfma_f32_16x16x32_bf16 v[16:19], v[124:127], v[228:231], v[16:19]
	v_mfma_f32_16x16x32_bf16 v[4:7], v[112:115], v[244:247], v[4:7]
	v_mfma_f32_16x16x32_bf16 v[0:3], v[124:127], v[244:247], v[0:3]
	v_mfma_f32_16x16x32_bf16 v[52:55], v[120:123], v[168:171], v[52:55]
	v_mfma_f32_16x16x32_bf16 v[48:51], v[132:135], v[168:171], v[48:51]
	v_mfma_f32_16x16x32_bf16 v[36:39], v[120:123], v[224:227], v[36:39]
	v_mfma_f32_16x16x32_bf16 v[32:35], v[132:135], v[224:227], v[32:35]
	v_mfma_f32_16x16x32_bf16 v[20:23], v[120:123], v[232:235], v[20:23]
	v_mfma_f32_16x16x32_bf16 v[16:19], v[132:135], v[232:235], v[16:19]
	v_mfma_f32_16x16x32_bf16 v[4:7], v[120:123], v[248:251], v[4:7]
	v_mfma_f32_16x16x32_bf16 v[0:3], v[132:135], v[248:251], v[0:3]
	s_barrier
	s_add_i32 s6, 0, 0x18000
	s_add_i32 s7, 0, 0x1c000
	v_add_u32_e32 v108, s6, v190
	v_add_u32_e32 v132, s7, v190
	ds_read_b128 v[88:91], v108
	ds_read_b128 v[100:103], v108 offset:1024
	ds_read_b128 v[104:107], v108 offset:2048
	ds_read_b128 v[108:111], v108 offset:3072
	ds_read_b128 v[112:115], v132
	ds_read_b128 v[120:123], v132 offset:1024
	ds_read_b128 v[124:127], v132 offset:2048
	ds_read_b128 v[132:135], v132 offset:3072
	s_add_u32 s58, s58, 0x84000
	s_addc_u32 s59, s59, 0
	s_mov_b32 m0, s25
	v_lshl_add_u64 v[242:243], s[58:59], 0, v[136:137]
	ds_read_b128 v[164:167], v222 offset:32768
	ds_read_b128 v[168:171], v222 offset:33792
	ds_read_b128 v[182:185], v222 offset:34816
	ds_read_b128 v[224:227], v222 offset:35840
	ds_read_b128 v[228:231], v222 offset:36864
	ds_read_b128 v[232:235], v222 offset:37888
	ds_read_b128 v[244:247], v222 offset:38912
	ds_read_b128 v[248:251], v222 offset:39936
	global_load_lds_dwordx4 v[242:243], off
	v_lshl_add_u64 v[242:243], s[58:59], 0, v[174:175]
	s_mov_b32 m0, s76
	s_nop 0
	global_load_lds_dwordx4 v[242:243], off
	s_waitcnt vmcnt(8)
	s_waitcnt lgkmcnt(0)
	s_barrier
	s_waitcnt lgkmcnt(0)
	v_mfma_f32_16x16x32_bf16 v[160:163], v[88:91], v[164:167], v[160:163]
	v_mfma_f32_16x16x32_bf16 v[156:159], v[104:107], v[164:167], v[156:159]
	v_mfma_f32_16x16x32_bf16 v[144:147], v[88:91], v[182:185], v[144:147]
	v_mfma_f32_16x16x32_bf16 v[140:143], v[104:107], v[182:185], v[140:143]
	v_mfma_f32_16x16x32_bf16 v[96:99], v[88:91], v[228:231], v[96:99]
	v_mfma_f32_16x16x32_bf16 v[92:95], v[104:107], v[228:231], v[92:95]
	v_mfma_f32_16x16x32_bf16 v[76:79], v[88:91], v[244:247], v[76:79]
	v_mfma_f32_16x16x32_bf16 v[72:75], v[104:107], v[244:247], v[72:75]
	v_mfma_f32_16x16x32_bf16 v[160:163], v[100:103], v[168:171], v[160:163]
	v_mfma_f32_16x16x32_bf16 v[156:159], v[108:111], v[168:171], v[156:159]
	v_mfma_f32_16x16x32_bf16 v[144:147], v[100:103], v[224:227], v[144:147]
	v_mfma_f32_16x16x32_bf16 v[140:143], v[108:111], v[224:227], v[140:143]
	v_mfma_f32_16x16x32_bf16 v[96:99], v[100:103], v[232:235], v[96:99]
	v_mfma_f32_16x16x32_bf16 v[92:95], v[108:111], v[232:235], v[92:95]
	v_mfma_f32_16x16x32_bf16 v[76:79], v[100:103], v[248:251], v[76:79]
	v_mfma_f32_16x16x32_bf16 v[72:75], v[108:111], v[248:251], v[72:75]
	v_mfma_f32_16x16x32_bf16 v[152:155], v[112:115], v[164:167], v[152:155]
	v_mfma_f32_16x16x32_bf16 v[148:151], v[124:127], v[164:167], v[148:151]
	v_mfma_f32_16x16x32_bf16 v[128:131], v[112:115], v[182:185], v[128:131]
	v_mfma_f32_16x16x32_bf16 v[116:119], v[124:127], v[182:185], v[116:119]
	v_mfma_f32_16x16x32_bf16 v[84:87], v[112:115], v[228:231], v[84:87]
	v_mfma_f32_16x16x32_bf16 v[80:83], v[124:127], v[228:231], v[80:83]
	v_mfma_f32_16x16x32_bf16 v[68:71], v[112:115], v[244:247], v[68:71]
	v_mfma_f32_16x16x32_bf16 v[64:67], v[124:127], v[244:247], v[64:67]
	v_mfma_f32_16x16x32_bf16 v[152:155], v[120:123], v[168:171], v[152:155]
	v_mfma_f32_16x16x32_bf16 v[148:151], v[132:135], v[168:171], v[148:151]
	v_mfma_f32_16x16x32_bf16 v[128:131], v[120:123], v[224:227], v[128:131]
	v_mfma_f32_16x16x32_bf16 v[116:119], v[132:135], v[224:227], v[116:119]
	v_mfma_f32_16x16x32_bf16 v[84:87], v[120:123], v[232:235], v[84:87]
	v_mfma_f32_16x16x32_bf16 v[80:83], v[132:135], v[232:235], v[80:83]
	v_mfma_f32_16x16x32_bf16 v[68:71], v[120:123], v[248:251], v[68:71]
	v_mfma_f32_16x16x32_bf16 v[64:67], v[132:135], v[248:251], v[64:67]
	s_barrier
; #define PG8_STAGE(bufoff, gbase, voff) do { _Pragma("unroll") for (int _i = 0; _i < 2; ++_i) \
;         __builtin_amdgcn_global_load_lds((const unsigned*)((const char*)(gbase) + (voff)[_i]), (LAS unsigned*)(lds + (bufoff) + ldsw + _i * 8192), 16, 0, 0); } while (0)
; #define PG8_LDA(dst, b, h) do { _Pragma("unroll") for (int m = 0; m < 4; ++m) _Pragma("unroll") for (int k = 0; k < 2; ++k) dst[m][k] = *(const LAS bf16x8*)(lds + PG8_SA(b, h) + aoff + m * 2048 + k * 1024); } while (0)
; #define PG8_MMA(ai, bj, At, Bt) do { __builtin_amdgcn_s_setprio(1); _Pragma("unroll") for (int m = 0; m < 4; ++m) _Pragma("unroll") for (int n = 0; n < 2; ++n) _Pragma("unroll") for (int k = 0; k < 2; ++k) \
;         acc[ai][bj][m][n] = __builtin_amdgcn_mfma_f32_16x16x32_bf16(Bt[n][k], At[m][k], acc[ai][bj][m][n], 0, 0, 0); __builtin_amdgcn_s_setprio(0); } while (0)
; #define PG8_WAIT_V(n) asm volatile("s_waitcnt vmcnt(" #n ")" ::: "memory")
; #define PG8_WAIT_L(n) asm volatile("s_waitcnt lgkmcnt(" #n ")" ::: "memory")
; #define PG8_BAR __builtin_amdgcn_s_barrier()
; #define PG8_SCHED __builtin_amdgcn_sched_barrier(0)
; template <class Epi, bool ALIGN_EPI>
; __device__ __forceinline__ void gemm_phase(LAS unsigned char* lds, const Gemm g, int G, int cid, const Epi& E) {
;     ...
;             PG8_LDA(At, 1, 1); PG8_STAGE(PG8_SB(1, 0), b3, voffB); PG8_STAGE(PG8_SB(1, 1), b3 + hB, voffB); PG8_STAGE(PG8_SA(1, 0), a3, voffA);
;             PG8_WAIT_V(8); PG8_WAIT_L(0); PG8_BAR; PG8_MMA(1, 0, At, B0); PG8_MMA(1, 1, At, B1); PG8_BAR; PG8_SCHED;
	s_add_u32 s58, s56, 0xc0000
	s_addc_u32 s59, s57, 0
	s_add_i32 s6, s6, s0
	v_lshl_add_u64 v[242:243], s[58:59], 0, v[172:173]
	s_mov_b32 m0, s6
	ds_read_b128 v[164:167], v222 offset:49152
	ds_read_b128 v[168:171], v222 offset:50176
	ds_read_b128 v[182:185], v222 offset:51200
	ds_read_b128 v[224:227], v222 offset:52224
	ds_read_b128 v[228:231], v222 offset:53248
	ds_read_b128 v[232:235], v222 offset:54272
	ds_read_b128 v[244:247], v222 offset:55296
	ds_read_b128 v[248:251], v222 offset:56320
	global_load_lds_dwordx4 v[242:243], off
	s_add_i32 m0, s6, 0x2000
	s_add_u32 s56, s56, 0xc2000
	v_lshl_add_u64 v[242:243], s[58:59], 0, v[176:177]
	s_addc_u32 s57, s57, 0
	s_add_i32 s6, s7, s0
	global_load_lds_dwordx4 v[242:243], off
	v_lshl_add_u64 v[242:243], s[56:57], 0, v[172:173]
	s_mov_b32 m0, s6
	v_lshl_add_u64 v[198:199], v[198:199], 0, s[36:37]
	global_load_lds_dwordx4 v[242:243], off
	v_lshl_add_u64 v[242:243], s[56:57], 0, v[176:177]
	s_add_i32 m0, s6, 0x2000
	s_nop 0
	global_load_lds_dwordx4 v[242:243], off
	s_mov_b32 m0, s78
	s_nop 0
	global_load_lds_dwordx4 v[198:199], off
	v_lshl_add_u64 v[198:199], v[200:201], 0, s[36:37]
	s_mov_b32 m0, s79
	s_nop 0
	global_load_lds_dwordx4 v[198:199], off
	s_waitcnt vmcnt(8)
	s_waitcnt lgkmcnt(0)
	s_barrier
	s_waitcnt lgkmcnt(0)
	v_mfma_f32_16x16x32_bf16 v[60:63], v[88:91], v[164:167], v[60:63]
	v_mfma_f32_16x16x32_bf16 v[56:59], v[104:107], v[164:167], v[56:59]
	v_mfma_f32_16x16x32_bf16 v[44:47], v[88:91], v[182:185], v[44:47]
	v_mfma_f32_16x16x32_bf16 v[40:43], v[104:107], v[182:185], v[40:43]
	v_mfma_f32_16x16x32_bf16 v[28:31], v[88:91], v[228:231], v[28:31]
	v_mfma_f32_16x16x32_bf16 v[24:27], v[104:107], v[228:231], v[24:27]
	v_mfma_f32_16x16x32_bf16 v[12:15], v[88:91], v[244:247], v[12:15]
	v_mfma_f32_16x16x32_bf16 v[8:11], v[104:107], v[244:247], v[8:11]
	v_mfma_f32_16x16x32_bf16 v[60:63], v[100:103], v[168:171], v[60:63]
	v_mfma_f32_16x16x32_bf16 v[56:59], v[108:111], v[168:171], v[56:59]
	v_mfma_f32_16x16x32_bf16 v[44:47], v[100:103], v[224:227], v[44:47]
	v_mfma_f32_16x16x32_bf16 v[40:43], v[108:111], v[224:227], v[40:43]
	v_mfma_f32_16x16x32_bf16 v[28:31], v[100:103], v[232:235], v[28:31]
	v_mfma_f32_16x16x32_bf16 v[24:27], v[108:111], v[232:235], v[24:27]
	v_mfma_f32_16x16x32_bf16 v[12:15], v[100:103], v[248:251], v[12:15]
	v_mfma_f32_16x16x32_bf16 v[8:11], v[108:111], v[248:251], v[8:11]
	v_mfma_f32_16x16x32_bf16 v[52:55], v[112:115], v[164:167], v[52:55]
	v_mfma_f32_16x16x32_bf16 v[48:51], v[124:127], v[164:167], v[48:51]
	v_mfma_f32_16x16x32_bf16 v[36:39], v[112:115], v[182:185], v[36:39]
	v_mfma_f32_16x16x32_bf16 v[32:35], v[124:127], v[182:185], v[32:35]
	v_mfma_f32_16x16x32_bf16 v[20:23], v[112:115], v[228:231], v[20:23]
	v_mfma_f32_16x16x32_bf16 v[16:19], v[124:127], v[228:231], v[16:19]
	v_mfma_f32_16x16x32_bf16 v[4:7], v[112:115], v[244:247], v[4:7]
	v_mfma_f32_16x16x32_bf16 v[0:3], v[124:127], v[244:247], v[0:3]
	v_mfma_f32_16x16x32_bf16 v[52:55], v[120:123], v[168:171], v[52:55]
	v_mfma_f32_16x16x32_bf16 v[48:51], v[132:135], v[168:171], v[48:51]
	v_mfma_f32_16x16x32_bf16 v[36:39], v[120:123], v[224:227], v[36:39]
	v_mfma_f32_16x16x32_bf16 v[32:35], v[132:135], v[224:227], v[32:35]
	v_mfma_f32_16x16x32_bf16 v[20:23], v[120:123], v[232:235], v[20:23]
	v_mfma_f32_16x16x32_bf16 v[16:19], v[132:135], v[232:235], v[16:19]
	v_mfma_f32_16x16x32_bf16 v[4:7], v[120:123], v[248:251], v[4:7]
	v_mfma_f32_16x16x32_bf16 v[0:3], v[132:135], v[248:251], v[0:3]
	s_barrier
	s_add_i32 s30, s30, 2
	s_add_u32 s54, s54, 0x180000
	s_addc_u32 s55, s55, 0
	s_cmp_gt_u32 s30, 29
	s_mov_b64 s[72:73], s[74:75]
	s_cbranch_scc1 .LBB0_269

; #define PG8_STAGE(bufoff, gbase, voff) do { _Pragma("unroll") for (int _i = 0; _i < 2; ++_i) \
;         __builtin_amdgcn_global_load_lds((const unsigned*)((const char*)(gbase) + (voff)[_i]), (LAS unsigned*)(lds + (bufoff) + ldsw + _i * 8192), 16, 0, 0); } while (0)
; #define PG8_LDA(dst, b, h) do { _Pragma("unroll") for (int m = 0; m < 4; ++m) _Pragma("unroll") for (int k = 0; k < 2; ++k) dst[m][k] = *(const LAS bf16x8*)(lds + PG8_SA(b, h) + aoff + m * 2048 + k * 1024); } while (0)
; #define PG8_LDB(dst, b, h) do { _Pragma("unroll") for (int n = 0; n < 2; ++n) _Pragma("unroll") for (int k = 0; k < 2; ++k) dst[n][k] = *(const LAS bf16x8*)(lds + PG8_SB(b, h) + boff + n * 2048 + k * 1024); } while (0)
; #define PG8_MMA(ai, bj, At, Bt) do { __builtin_amdgcn_s_setprio(1); _Pragma("unroll") for (int m = 0; m < 4; ++m) _Pragma("unroll") for (int n = 0; n < 2; ++n) _Pragma("unroll") for (int k = 0; k < 2; ++k) \
;         acc[ai][bj][m][n] = __builtin_amdgcn_mfma_f32_16x16x32_bf16(Bt[n][k], At[m][k], acc[ai][bj][m][n], 0, 0, 0); __builtin_amdgcn_s_setprio(0); } while (0)
; #define PG8_WAIT_V(n) asm volatile("s_waitcnt vmcnt(" #n ")" ::: "memory")
; #define PG8_WAIT_L(n) asm volatile("s_waitcnt lgkmcnt(" #n ")" ::: "memory")
; #define PG8_BAR __builtin_amdgcn_s_barrier()
; #define PG8_SCHED __builtin_amdgcn_sched_barrier(0)
; template <class Epi, bool ALIGN_EPI>
; __device__ __forceinline__ void gemm_phase(LAS unsigned char* lds, const Gemm g, int G, int cid, const Epi& E) {
;     ...
;             const char* a1 = cA + (size_t)(t + 1) * kA;
;             const char* a2 = last ? nA : cA + (size_t)(t + 2) * kA; const char* b2 = last ? nB : cB + (size_t)(t + 2) * kB;
;             const char* a3 = a2 + kA; const char* b3 = b2 + kB;
;             PG8_LDB(B0, 0, 0); PG8_LDB(B1, 0, 1); PG8_SCHED; PG8_LDA(At, 0, 0); PG8_STAGE(PG8_SA(1, 1), a1 + hA, voffA);
;             PG8_WAIT_V(8); PG8_WAIT_L(0); PG8_BAR; PG8_MMA(0, 0, At, B0); PG8_MMA(0, 1, At, B1); PG8_BAR; PG8_SCHED;
;             PG8_LDA(At, 0, 1); PG8_STAGE(PG8_SB(0, 0), b2, voffB); PG8_STAGE(PG8_SB(0, 1), b2 + hB, voffB); PG8_STAGE(PG8_SA(0, 0), a2, voffA);
;             PG8_WAIT_V(8); PG8_WAIT_L(0); PG8_BAR; PG8_MMA(1, 0, At, B0); PG8_MMA(1, 1, At, B1); PG8_BAR; PG8_SCHED;
.LBB0_727:
	s_add_u32 s42, s46, 0x100
	s_addc_u32 s43, s47, 0
	s_add_i32 s6, 0, 0x10000
	s_cmp_eq_u32 s77, 28
	s_cselect_b32 s51, s29, s43
	s_cselect_b32 s50, s28, s42
	s_cselect_b32 s49, s30, s76
	s_cselect_b32 s48, s74, s75
	s_add_i32 s7, 0, 0x14000
	v_add_u32_e32 v132, s6, v220
	v_add_u32_e32 v160, s7, v220
	ds_read_b128 v[112:115], v132
	ds_read_b128 v[116:119], v132 offset:1024
	ds_read_b128 v[128:131], v132 offset:2048
	ds_read_b128 v[132:135], v132 offset:3072
	ds_read_b128 v[140:143], v160
	ds_read_b128 v[144:147], v160 offset:1024
	ds_read_b128 v[156:159], v160 offset:2048
	ds_read_b128 v[160:163], v160 offset:3072
	v_lshl_add_u64 v[198:199], s[46:47], 0, v[184:185]
	s_add_i32 m0, s52, 0xc000
	ds_read_b128 v[164:167], v222
	ds_read_b128 v[168:171], v222 offset:1024
	ds_read_b128 v[172:175], v222 offset:2048
	ds_read_b128 v[176:179], v222 offset:3072
	ds_read_b128 v[188:191], v222 offset:4096
	ds_read_b128 v[206:209], v222 offset:5120
	ds_read_b128 v[210:213], v222 offset:6144
	ds_read_b128 v[214:217], v222 offset:7168
	global_load_lds_dwordx4 v[198:199], off
	v_lshl_add_u64 v[198:199], s[46:47], 0, v[186:187]
	s_add_i32 m0, s52, 0xe000
	s_nop 0
	global_load_lds_dwordx4 v[198:199], off
	s_add_i32 vcc_lo, s77, 2
	s_lshl_b32 vcc_lo, vcc_lo, 16
	s_lshl_b32 vcc_hi, s13, 21
	s_add_i32 vcc_lo, vcc_lo, vcc_hi
	s_lshl_b32 vcc_hi, s25, 4
	s_add_i32 vcc_lo, vcc_lo, vcc_hi
	s_lshl_b32 vcc_hi, s12, 10
	s_add_i32 vcc_lo, vcc_lo, vcc_hi
	s_add_u32 vcc_lo, s22, vcc_lo
	s_addc_u32 vcc_hi, s23, 0
	s_mov_b32 m0, 0x22c00
	s_nop 0
	global_load_lds_dwordx4 v224, vcc
	s_waitcnt vmcnt(9)
	s_waitcnt lgkmcnt(0)
	s_barrier
	s_waitcnt lgkmcnt(0)
	v_mfma_f32_16x16x32_bf16 v[152:155], v[112:115], v[164:167], v[152:155]
	v_mfma_f32_16x16x32_bf16 v[148:151], v[128:131], v[164:167], v[148:151]
	v_mfma_f32_16x16x32_bf16 v[108:111], v[112:115], v[172:175], v[108:111]
	v_mfma_f32_16x16x32_bf16 v[104:107], v[128:131], v[172:175], v[104:107]
	v_mfma_f32_16x16x32_bf16 v[92:95], v[112:115], v[188:191], v[92:95]
	v_mfma_f32_16x16x32_bf16 v[88:91], v[128:131], v[188:191], v[88:91]
	v_mfma_f32_16x16x32_bf16 v[76:79], v[112:115], v[210:213], v[76:79]
	v_mfma_f32_16x16x32_bf16 v[72:75], v[128:131], v[210:213], v[72:75]
	v_mfma_f32_16x16x32_bf16 v[152:155], v[116:119], v[168:171], v[152:155]
	v_mfma_f32_16x16x32_bf16 v[148:151], v[132:135], v[168:171], v[148:151]
	v_mfma_f32_16x16x32_bf16 v[108:111], v[116:119], v[176:179], v[108:111]
	v_mfma_f32_16x16x32_bf16 v[104:107], v[132:135], v[176:179], v[104:107]
	v_mfma_f32_16x16x32_bf16 v[92:95], v[116:119], v[206:209], v[92:95]
	v_mfma_f32_16x16x32_bf16 v[88:91], v[132:135], v[206:209], v[88:91]
	v_mfma_f32_16x16x32_bf16 v[76:79], v[116:119], v[214:217], v[76:79]
	v_mfma_f32_16x16x32_bf16 v[72:75], v[132:135], v[214:217], v[72:75]
	v_mfma_f32_16x16x32_bf16 v[124:127], v[140:143], v[164:167], v[124:127]
	v_mfma_f32_16x16x32_bf16 v[120:123], v[156:159], v[164:167], v[120:123]
	v_mfma_f32_16x16x32_bf16 v[100:103], v[140:143], v[172:175], v[100:103]
	v_mfma_f32_16x16x32_bf16 v[96:99], v[156:159], v[172:175], v[96:99]
	v_mfma_f32_16x16x32_bf16 v[84:87], v[140:143], v[188:191], v[84:87]
	v_mfma_f32_16x16x32_bf16 v[80:83], v[156:159], v[188:191], v[80:83]
	v_mfma_f32_16x16x32_bf16 v[68:71], v[140:143], v[210:213], v[68:71]
	v_mfma_f32_16x16x32_bf16 v[64:67], v[156:159], v[210:213], v[64:67]
	v_mfma_f32_16x16x32_bf16 v[124:127], v[144:147], v[168:171], v[124:127]
	v_mfma_f32_16x16x32_bf16 v[120:123], v[160:163], v[168:171], v[120:123]
	v_mfma_f32_16x16x32_bf16 v[100:103], v[144:147], v[176:179], v[100:103]
	v_mfma_f32_16x16x32_bf16 v[96:99], v[160:163], v[176:179], v[96:99]
	v_mfma_f32_16x16x32_bf16 v[84:87], v[144:147], v[206:209], v[84:87]
	v_mfma_f32_16x16x32_bf16 v[80:83], v[160:163], v[206:209], v[80:83]
	v_mfma_f32_16x16x32_bf16 v[68:71], v[144:147], v[214:217], v[68:71]
	v_mfma_f32_16x16x32_bf16 v[64:67], v[160:163], v[214:217], v[64:67]
	s_barrier
	s_add_i32 s6, s6, s25
	v_lshl_add_u64 v[198:199], s[48:49], 0, v[138:139]
	s_mov_b32 m0, s6
	ds_read_b128 v[164:167], v222 offset:16384
	ds_read_b128 v[168:171], v222 offset:17408
	ds_read_b128 v[172:175], v222 offset:18432
	ds_read_b128 v[176:179], v222 offset:19456
	ds_read_b128 v[188:191], v222 offset:20480
	ds_read_b128 v[206:209], v222 offset:21504
	ds_read_b128 v[210:213], v222 offset:22528
	ds_read_b128 v[214:217], v222 offset:23552
	global_load_lds_dwordx4 v[198:199], off
	s_add_i32 m0, s6, 0x2000
	s_add_u32 s46, s48, 0x2000
	v_lshl_add_u64 v[198:199], s[48:49], 0, v[136:137]
	s_addc_u32 s47, s49, 0
	s_add_i32 s6, s7, s25
	global_load_lds_dwordx4 v[198:199], off
	v_lshl_add_u64 v[198:199], s[46:47], 0, v[138:139]
	s_mov_b32 m0, s6
	v_lshl_add_u64 v[200:201], s[50:51], 0, v[180:181]
	global_load_lds_dwordx4 v[198:199], off
	v_lshl_add_u64 v[198:199], s[46:47], 0, v[136:137]
	s_add_i32 m0, s6, 0x2000
	s_nop 0
	global_load_lds_dwordx4 v[198:199], off
	v_lshl_add_u64 v[198:199], s[50:51], 0, v[182:183]
	s_mov_b32 m0, s52
	s_nop 0
	global_load_lds_dwordx4 v[198:199], off
	s_mov_b32 m0, s53
	s_nop 0
	global_load_lds_dwordx4 v[200:201], off
	s_waitcnt vmcnt(9)
	s_waitcnt lgkmcnt(0)
	s_barrier
; #define PG8_STAGE(bufoff, gbase, voff) do { _Pragma("unroll") for (int _i = 0; _i < 2; ++_i) \
;         __builtin_amdgcn_global_load_lds((const unsigned*)((const char*)(gbase) + (voff)[_i]), (LAS unsigned*)(lds + (bufoff) + ldsw + _i * 8192), 16, 0, 0); } while (0)
; #define PG8_LDA(dst, b, h) do { _Pragma("unroll") for (int m = 0; m < 4; ++m) _Pragma("unroll") for (int k = 0; k < 2; ++k) dst[m][k] = *(const LAS bf16x8*)(lds + PG8_SA(b, h) + aoff + m * 2048 + k * 1024); } while (0)
; #define PG8_LDB(dst, b, h) do { _Pragma("unroll") for (int n = 0; n < 2; ++n) _Pragma("unroll") for (int k = 0; k < 2; ++k) dst[n][k] = *(const LAS bf16x8*)(lds + PG8_SB(b, h) + boff + n * 2048 + k * 1024); } while (0)
; #define PG8_MMA(ai, bj, At, Bt) do { __builtin_amdgcn_s_setprio(1); _Pragma("unroll") for (int m = 0; m < 4; ++m) _Pragma("unroll") for (int n = 0; n < 2; ++n) _Pragma("unroll") for (int k = 0; k < 2; ++k) \
;         acc[ai][bj][m][n] = __builtin_amdgcn_mfma_f32_16x16x32_bf16(Bt[n][k], At[m][k], acc[ai][bj][m][n], 0, 0, 0); __builtin_amdgcn_s_setprio(0); } while (0)
; #define PG8_WAIT_V(n) asm volatile("s_waitcnt vmcnt(" #n ")" ::: "memory")
; #define PG8_WAIT_L(n) asm volatile("s_waitcnt lgkmcnt(" #n ")" ::: "memory")
; #define PG8_BAR __builtin_amdgcn_s_barrier()
; #define PG8_SCHED __builtin_amdgcn_sched_barrier(0)
; template <class Epi, bool ALIGN_EPI>
; __device__ __forceinline__ void gemm_phase(LAS unsigned char* lds, const Gemm g, int G, int cid, const Epi& E) {
;     ...
;             PG8_WAIT_V(8); PG8_WAIT_L(0); PG8_BAR; PG8_MMA(1, 0, At, B0); PG8_MMA(1, 1, At, B1); PG8_BAR; PG8_SCHED;
;             PG8_LDB(B0, 1, 0); PG8_LDB(B1, 1, 1); PG8_SCHED; PG8_LDA(At, 1, 0); PG8_STAGE(PG8_SA(0, 1), a2 + hA, voffA);
;             PG8_WAIT_V(8); PG8_WAIT_L(0); PG8_BAR; PG8_MMA(0, 0, At, B0); PG8_MMA(0, 1, At, B1); PG8_BAR; PG8_SCHED;
	s_waitcnt lgkmcnt(0)
	v_mfma_f32_16x16x32_bf16 v[60:63], v[112:115], v[164:167], v[60:63]
	v_mfma_f32_16x16x32_bf16 v[56:59], v[128:131], v[164:167], v[56:59]
	v_mfma_f32_16x16x32_bf16 v[44:47], v[112:115], v[172:175], v[44:47]
	v_mfma_f32_16x16x32_bf16 v[40:43], v[128:131], v[172:175], v[40:43]
	v_mfma_f32_16x16x32_bf16 v[28:31], v[112:115], v[188:191], v[28:31]
	v_mfma_f32_16x16x32_bf16 v[24:27], v[128:131], v[188:191], v[24:27]
	v_mfma_f32_16x16x32_bf16 v[12:15], v[112:115], v[210:213], v[12:15]
	v_mfma_f32_16x16x32_bf16 v[8:11], v[128:131], v[210:213], v[8:11]
	v_mfma_f32_16x16x32_bf16 v[60:63], v[116:119], v[168:171], v[60:63]
	v_mfma_f32_16x16x32_bf16 v[56:59], v[132:135], v[168:171], v[56:59]
	v_mfma_f32_16x16x32_bf16 v[44:47], v[116:119], v[176:179], v[44:47]
	v_mfma_f32_16x16x32_bf16 v[40:43], v[132:135], v[176:179], v[40:43]
	v_mfma_f32_16x16x32_bf16 v[28:31], v[116:119], v[206:209], v[28:31]
	v_mfma_f32_16x16x32_bf16 v[24:27], v[132:135], v[206:209], v[24:27]
	v_mfma_f32_16x16x32_bf16 v[12:15], v[116:119], v[214:217], v[12:15]
	v_mfma_f32_16x16x32_bf16 v[8:11], v[132:135], v[214:217], v[8:11]
	v_mfma_f32_16x16x32_bf16 v[52:55], v[140:143], v[164:167], v[52:55]
	v_mfma_f32_16x16x32_bf16 v[48:51], v[156:159], v[164:167], v[48:51]
	v_mfma_f32_16x16x32_bf16 v[36:39], v[140:143], v[172:175], v[36:39]
	v_mfma_f32_16x16x32_bf16 v[32:35], v[156:159], v[172:175], v[32:35]
	v_mfma_f32_16x16x32_bf16 v[20:23], v[140:143], v[188:191], v[20:23]
	v_mfma_f32_16x16x32_bf16 v[16:19], v[156:159], v[188:191], v[16:19]
	v_mfma_f32_16x16x32_bf16 v[4:7], v[140:143], v[210:213], v[4:7]
	v_mfma_f32_16x16x32_bf16 v[0:3], v[156:159], v[210:213], v[0:3]
	v_mfma_f32_16x16x32_bf16 v[52:55], v[144:147], v[168:171], v[52:55]
	v_mfma_f32_16x16x32_bf16 v[48:51], v[160:163], v[168:171], v[48:51]
	v_mfma_f32_16x16x32_bf16 v[36:39], v[144:147], v[176:179], v[36:39]
	v_mfma_f32_16x16x32_bf16 v[32:35], v[160:163], v[176:179], v[32:35]
	v_mfma_f32_16x16x32_bf16 v[20:23], v[144:147], v[206:209], v[20:23]
	v_mfma_f32_16x16x32_bf16 v[16:19], v[160:163], v[206:209], v[16:19]
	v_mfma_f32_16x16x32_bf16 v[4:7], v[144:147], v[214:217], v[4:7]
	v_mfma_f32_16x16x32_bf16 v[0:3], v[160:163], v[214:217], v[0:3]
	s_barrier
	s_add_i32 s6, 0, 0x18000
	s_add_i32 s7, 0, 0x1c000
	v_add_u32_e32 v132, s6, v220
	v_add_u32_e32 v160, s7, v220
	ds_read_b128 v[112:115], v132
	ds_read_b128 v[116:119], v132 offset:1024
	ds_read_b128 v[128:131], v132 offset:2048
	ds_read_b128 v[132:135], v132 offset:3072
	ds_read_b128 v[140:143], v160
	ds_read_b128 v[144:147], v160 offset:1024
	ds_read_b128 v[156:159], v160 offset:2048
	ds_read_b128 v[160:163], v160 offset:3072
	s_add_u32 s46, s50, 0x84000
	s_addc_u32 s47, s51, 0
	s_mov_b32 m0, s54
	v_lshl_add_u64 v[218:219], s[46:47], 0, v[182:183]
	ds_read_b128 v[164:167], v222 offset:32768
	ds_read_b128 v[168:171], v222 offset:33792
	ds_read_b128 v[172:175], v222 offset:34816
	ds_read_b128 v[176:179], v222 offset:35840
	ds_read_b128 v[188:191], v222 offset:36864
	ds_read_b128 v[206:209], v222 offset:37888
	ds_read_b128 v[210:213], v222 offset:38912
	ds_read_b128 v[214:217], v222 offset:39936
	global_load_lds_dwordx4 v[218:219], off
	v_lshl_add_u64 v[218:219], s[46:47], 0, v[180:181]
	s_mov_b32 m0, s55
	s_nop 0
	global_load_lds_dwordx4 v[218:219], off
	s_add_u32 vcc_lo, vcc_lo, 0x2000
	s_addc_u32 vcc_hi, vcc_hi, 0
	s_mov_b32 m0, 0x22c00
	s_nop 0
	global_load_lds_dwordx4 v224, vcc
	s_waitcnt vmcnt(9)
	s_waitcnt lgkmcnt(0)
	s_barrier
	s_waitcnt lgkmcnt(0)
	v_mfma_f32_16x16x32_bf16 v[152:155], v[112:115], v[164:167], v[152:155]
	v_mfma_f32_16x16x32_bf16 v[148:151], v[128:131], v[164:167], v[148:151]
	v_mfma_f32_16x16x32_bf16 v[108:111], v[112:115], v[172:175], v[108:111]
	v_mfma_f32_16x16x32_bf16 v[104:107], v[128:131], v[172:175], v[104:107]
	v_mfma_f32_16x16x32_bf16 v[92:95], v[112:115], v[188:191], v[92:95]
	v_mfma_f32_16x16x32_bf16 v[88:91], v[128:131], v[188:191], v[88:91]
	v_mfma_f32_16x16x32_bf16 v[76:79], v[112:115], v[210:213], v[76:79]
	v_mfma_f32_16x16x32_bf16 v[72:75], v[128:131], v[210:213], v[72:75]
	v_mfma_f32_16x16x32_bf16 v[152:155], v[116:119], v[168:171], v[152:155]
	v_mfma_f32_16x16x32_bf16 v[148:151], v[132:135], v[168:171], v[148:151]
	v_mfma_f32_16x16x32_bf16 v[108:111], v[116:119], v[176:179], v[108:111]
	v_mfma_f32_16x16x32_bf16 v[104:107], v[132:135], v[176:179], v[104:107]
	v_mfma_f32_16x16x32_bf16 v[92:95], v[116:119], v[206:209], v[92:95]
	v_mfma_f32_16x16x32_bf16 v[88:91], v[132:135], v[206:209], v[88:91]
	v_mfma_f32_16x16x32_bf16 v[76:79], v[116:119], v[214:217], v[76:79]
	v_mfma_f32_16x16x32_bf16 v[72:75], v[132:135], v[214:217], v[72:75]
	v_mfma_f32_16x16x32_bf16 v[124:127], v[140:143], v[164:167], v[124:127]
	v_mfma_f32_16x16x32_bf16 v[120:123], v[156:159], v[164:167], v[120:123]
	v_mfma_f32_16x16x32_bf16 v[100:103], v[140:143], v[172:175], v[100:103]
	v_mfma_f32_16x16x32_bf16 v[96:99], v[156:159], v[172:175], v[96:99]
	v_mfma_f32_16x16x32_bf16 v[84:87], v[140:143], v[188:191], v[84:87]
	v_mfma_f32_16x16x32_bf16 v[80:83], v[156:159], v[188:191], v[80:83]
	v_mfma_f32_16x16x32_bf16 v[68:71], v[140:143], v[210:213], v[68:71]
	v_mfma_f32_16x16x32_bf16 v[64:67], v[156:159], v[210:213], v[64:67]
	v_mfma_f32_16x16x32_bf16 v[124:127], v[144:147], v[168:171], v[124:127]
	v_mfma_f32_16x16x32_bf16 v[120:123], v[160:163], v[168:171], v[120:123]
	v_mfma_f32_16x16x32_bf16 v[100:103], v[144:147], v[176:179], v[100:103]
	v_mfma_f32_16x16x32_bf16 v[96:99], v[160:163], v[176:179], v[96:99]
	v_mfma_f32_16x16x32_bf16 v[84:87], v[144:147], v[206:209], v[84:87]
	v_mfma_f32_16x16x32_bf16 v[80:83], v[160:163], v[206:209], v[80:83]
	v_mfma_f32_16x16x32_bf16 v[68:71], v[144:147], v[214:217], v[68:71]
	v_mfma_f32_16x16x32_bf16 v[64:67], v[160:163], v[214:217], v[64:67]
	s_barrier
; #define PG8_STAGE(bufoff, gbase, voff) do { _Pragma("unroll") for (int _i = 0; _i < 2; ++_i) \
;         __builtin_amdgcn_global_load_lds((const unsigned*)((const char*)(gbase) + (voff)[_i]), (LAS unsigned*)(lds + (bufoff) + ldsw + _i * 8192), 16, 0, 0); } while (0)
; #define PG8_LDA(dst, b, h) do { _Pragma("unroll") for (int m = 0; m < 4; ++m) _Pragma("unroll") for (int k = 0; k < 2; ++k) dst[m][k] = *(const LAS bf16x8*)(lds + PG8_SA(b, h) + aoff + m * 2048 + k * 1024); } while (0)
; #define PG8_MMA(ai, bj, At, Bt) do { __builtin_amdgcn_s_setprio(1); _Pragma("unroll") for (int m = 0; m < 4; ++m) _Pragma("unroll") for (int n = 0; n < 2; ++n) _Pragma("unroll") for (int k = 0; k < 2; ++k) \
;         acc[ai][bj][m][n] = __builtin_amdgcn_mfma_f32_16x16x32_bf16(Bt[n][k], At[m][k], acc[ai][bj][m][n], 0, 0, 0); __builtin_amdgcn_s_setprio(0); } while (0)
; #define PG8_WAIT_V(n) asm volatile("s_waitcnt vmcnt(" #n ")" ::: "memory")
; #define PG8_WAIT_L(n) asm volatile("s_waitcnt lgkmcnt(" #n ")" ::: "memory")
; #define PG8_BAR __builtin_amdgcn_s_barrier()
; #define PG8_SCHED __builtin_amdgcn_sched_barrier(0)
; template <class Epi, bool ALIGN_EPI>
; __device__ __forceinline__ void gemm_phase(LAS unsigned char* lds, const Gemm g, int G, int cid, const Epi& E) {
;     ...
;             PG8_LDA(At, 1, 1); PG8_STAGE(PG8_SB(1, 0), b3, voffB); PG8_STAGE(PG8_SB(1, 1), b3 + hB, voffB); PG8_STAGE(PG8_SA(1, 0), a3, voffA);
;             PG8_WAIT_V(8); PG8_WAIT_L(0); PG8_BAR; PG8_MMA(1, 0, At, B0); PG8_MMA(1, 1, At, B1); PG8_BAR; PG8_SCHED;
	s_add_u32 s46, s48, 0x40000
	s_addc_u32 s47, s49, 0
	s_add_i32 s6, s6, s25
	v_lshl_add_u64 v[218:219], s[46:47], 0, v[138:139]
	s_mov_b32 m0, s6
	ds_read_b128 v[164:167], v222 offset:49152
	ds_read_b128 v[168:171], v222 offset:50176
	ds_read_b128 v[172:175], v222 offset:51200
	ds_read_b128 v[176:179], v222 offset:52224
	ds_read_b128 v[188:191], v222 offset:53248
	ds_read_b128 v[206:209], v222 offset:54272
	ds_read_b128 v[210:213], v222 offset:55296
	ds_read_b128 v[214:217], v222 offset:56320
	global_load_lds_dwordx4 v[218:219], off
	s_add_i32 m0, s6, 0x2000
	v_lshl_add_u64 v[218:219], s[46:47], 0, v[136:137]
	s_add_u32 s46, s48, 0x42000
	s_addc_u32 s47, s49, 0
	s_add_i32 s6, s7, s25
	global_load_lds_dwordx4 v[218:219], off
	v_lshl_add_u64 v[218:219], s[46:47], 0, v[138:139]
	s_mov_b32 m0, s6
	v_lshl_add_u64 v[198:199], v[198:199], 0, s[36:37]
	global_load_lds_dwordx4 v[218:219], off
	v_lshl_add_u64 v[218:219], s[46:47], 0, v[136:137]
	s_add_i32 m0, s6, 0x2000
	s_nop 0
	global_load_lds_dwordx4 v[218:219], off
	s_mov_b32 m0, s58
	s_nop 0
	global_load_lds_dwordx4 v[198:199], off
	v_lshl_add_u64 v[198:199], v[200:201], 0, s[36:37]
	s_mov_b32 m0, s59
	s_nop 0
	global_load_lds_dwordx4 v[198:199], off
	s_waitcnt vmcnt(9)
	s_waitcnt lgkmcnt(0)
	s_barrier
	s_waitcnt lgkmcnt(0)
	v_mfma_f32_16x16x32_bf16 v[60:63], v[112:115], v[164:167], v[60:63]
	v_mfma_f32_16x16x32_bf16 v[56:59], v[128:131], v[164:167], v[56:59]
	v_mfma_f32_16x16x32_bf16 v[44:47], v[112:115], v[172:175], v[44:47]
	v_mfma_f32_16x16x32_bf16 v[40:43], v[128:131], v[172:175], v[40:43]
	v_mfma_f32_16x16x32_bf16 v[28:31], v[112:115], v[188:191], v[28:31]
	v_mfma_f32_16x16x32_bf16 v[24:27], v[128:131], v[188:191], v[24:27]
	v_mfma_f32_16x16x32_bf16 v[12:15], v[112:115], v[210:213], v[12:15]
	v_mfma_f32_16x16x32_bf16 v[8:11], v[128:131], v[210:213], v[8:11]
	v_mfma_f32_16x16x32_bf16 v[60:63], v[116:119], v[168:171], v[60:63]
	v_mfma_f32_16x16x32_bf16 v[56:59], v[132:135], v[168:171], v[56:59]
	v_mfma_f32_16x16x32_bf16 v[44:47], v[116:119], v[176:179], v[44:47]
	v_mfma_f32_16x16x32_bf16 v[40:43], v[132:135], v[176:179], v[40:43]
	v_mfma_f32_16x16x32_bf16 v[28:31], v[116:119], v[206:209], v[28:31]
	v_mfma_f32_16x16x32_bf16 v[24:27], v[132:135], v[206:209], v[24:27]
	v_mfma_f32_16x16x32_bf16 v[12:15], v[116:119], v[214:217], v[12:15]
	v_mfma_f32_16x16x32_bf16 v[8:11], v[132:135], v[214:217], v[8:11]
	v_mfma_f32_16x16x32_bf16 v[52:55], v[140:143], v[164:167], v[52:55]
	v_mfma_f32_16x16x32_bf16 v[48:51], v[156:159], v[164:167], v[48:51]
	v_mfma_f32_16x16x32_bf16 v[36:39], v[140:143], v[172:175], v[36:39]
	v_mfma_f32_16x16x32_bf16 v[32:35], v[156:159], v[172:175], v[32:35]
	v_mfma_f32_16x16x32_bf16 v[20:23], v[140:143], v[188:191], v[20:23]
	v_mfma_f32_16x16x32_bf16 v[16:19], v[156:159], v[188:191], v[16:19]
	v_mfma_f32_16x16x32_bf16 v[4:7], v[140:143], v[210:213], v[4:7]
	v_mfma_f32_16x16x32_bf16 v[0:3], v[156:159], v[210:213], v[0:3]
	v_mfma_f32_16x16x32_bf16 v[52:55], v[144:147], v[168:171], v[52:55]
	v_mfma_f32_16x16x32_bf16 v[48:51], v[160:163], v[168:171], v[48:51]
	v_mfma_f32_16x16x32_bf16 v[36:39], v[144:147], v[176:179], v[36:39]
	v_mfma_f32_16x16x32_bf16 v[32:35], v[160:163], v[176:179], v[32:35]
	v_mfma_f32_16x16x32_bf16 v[20:23], v[144:147], v[206:209], v[20:23]
	v_mfma_f32_16x16x32_bf16 v[16:19], v[160:163], v[206:209], v[16:19]
	v_mfma_f32_16x16x32_bf16 v[4:7], v[144:147], v[214:217], v[4:7]
	v_mfma_f32_16x16x32_bf16 v[0:3], v[160:163], v[214:217], v[0:3]
	s_barrier
	s_add_i32 s77, s77, 2
	s_add_u32 s75, s75, 0x80000
	s_addc_u32 s76, s76, 0
	s_cmp_gt_u32 s77, 29
	s_mov_b64 s[46:47], s[42:43]
	s_cbranch_scc0 .LBB0_727
; __device__ __forceinline__ unsigned cvt_pk_bf16(float lo, float hi) { unsigned r; asm volatile("v_cvt_pk_bf16_f32 %0, %1, %2" : "=v"(r) : "v"(lo), "v"(hi)); return r; }
;     __device__ __forceinline__ void operator()(const f32x4 (&acc)[2][2][4][2], const Unit& u, int wr, int wc, int fr, int fq, const LAS float*) const {
;     ...
;         for (int am = 0; am < NB; ++am) { const int ai = am / (NB / 2), m0 = (am % (NB / 2)) * MB;
;             f32x4 xo[4][2][2];
; #pragma unroll
;             for (int m = m0; m < m0 + MB; ++m) { const float* xr = Xs + (size_t)(row0 + ai * HALF + m * 16) * DM + col0;
; #pragma unroll
;                 for (int bj = 0; bj < 2; ++bj) { xo[m][bj][0] = *(const f32x4*)(xr + bj * HALF); xo[m][bj][1] = *(const f32x4*)(xr + bj * HALF + 4); } }
; #pragma unroll
;             for (int m = m0; m < m0 + MB; ++m) { const int row = row0 + ai * HALF + m * 16; float ss = 0.f;
;                 float* xr = X + (size_t)row * DM + col0; bf16_t* xb = XB + (size_t)row * ALD + col0;
; #pragma unroll
;                 for (int bj = 0; bj < 2; ++bj) { f32x4 x0 = xo[m][bj][0], x1 = xo[m][bj][1];
;                     if (HB) { x0 += (acc[ai][bj][m][0] + bv[bj][0]) * sv[bj][0]; x1 += (acc[ai][bj][m][1] + bv[bj][1]) * sv[bj][1]; } else { x0 += acc[ai][bj][m][0]; x1 += acc[ai][bj][m][1]; }
;                     *(f32x4*)(xr + bj * HALF) = x0; *(f32x4*)(xr + bj * HALF + 4) = x1;
;                     ss += (x0[0] * x0[0] + x0[1] * x0[1]) + (x0[2] * x0[2] + x0[3] * x0[3]) + (x1[0] * x1[0] + x1[1] * x1[1]) + (x1[2] * x1[2] + x1[3] * x1[3]);
;                     u32x4 w; w.x = cvt_pk_bf16(x0[0], x0[1]); w.y = cvt_pk_bf16(x0[2], x0[3]); w.z = cvt_pk_bf16(x1[0], x1[1]); w.w = cvt_pk_bf16(x1[2], x1[3]);
;                     if (feeds) *(u32x4*)(xb + bj * HALF) = w; }
;                 ss += __shfl_xor(ss, 16); ss += __shfl_xor(ss, 32);
;                 if (fq == 0 && feeds) part[(size_t)row * NPART + u.pn * 4 + wc] = ss; }
	v_lshl_or_b32 v188, s12, 8, v221
	v_lshl_add_u32 v190, s13, 8, v197
	v_ashrrev_i32_e32 v189, 31, v188
	v_lshlrev_b64 v[198:199], 2, v[188:189]
	v_ashrrev_i32_e32 v191, 31, v190
	v_lshl_add_u64 v[206:207], s[22:23], 0, v[198:199]
	v_lshlrev_b64 v[200:201], 13, v[190:191]
	v_lshl_add_u64 v[112:113], v[206:207], 0, v[200:201]
	global_load_dwordx4 v[224:227], v[112:113], off offset:16
	global_load_dwordx4 v[228:231], v[112:113], off
	global_load_dwordx4 v[232:235], v[112:113], off offset:528
	global_load_dwordx4 v[244:247], v[112:113], off offset:512
	v_or_b32_e32 v214, 16, v190
	v_ashrrev_i32_e32 v215, 31, v214
	v_or_b32_e32 v210, 32, v190
	v_or_b32_e32 v208, 48, v190
	v_lshlrev_b64 v[218:219], 13, v[214:215]
	v_ashrrev_i32_e32 v211, 31, v210
	v_ashrrev_i32_e32 v209, 31, v208
	v_lshl_add_u64 v[112:113], v[206:207], 0, v[218:219]
	v_lshlrev_b64 v[216:217], 13, v[210:211]
	v_lshlrev_b64 v[212:213], 13, v[208:209]
	global_load_dwordx4 v[172:175], v[112:113], off offset:16
	global_load_dwordx4 v[176:179], v[112:113], off
	global_load_dwordx4 v[164:167], v[112:113], off offset:528
	global_load_dwordx4 v[168:171], v[112:113], off offset:512
	v_lshl_add_u64 v[112:113], v[206:207], 0, v[216:217]
	v_lshl_add_u64 v[116:117], v[206:207], 0, v[212:213]
	global_load_dwordx4 v[156:159], v[112:113], off offset:16
	global_load_dwordx4 v[160:163], v[112:113], off
	global_load_dwordx4 v[128:131], v[112:113], off offset:528
	global_load_dwordx4 v[144:147], v[112:113], off offset:512
	global_load_dwordx4 v[132:135], v[116:117], off offset:16
	global_load_dwordx4 v[140:143], v[116:117], off
	s_nop 0
	global_load_dwordx4 v[112:115], v[116:117], off offset:528
	s_nop 0
	global_load_dwordx4 v[116:119], v[116:117], off offset:512
	v_lshl_add_u64 v[200:201], s[82:83], 0, v[200:201]
	v_lshl_add_u64 v[198:199], v[200:201], 0, v[198:199]
	v_mov_b64_e32 v[200:201], s[4:5]
	s_lshl_b32 s42, s12, 2
	v_mad_i64_i32 v[200:201], s[12:13], v190, s66, v[200:201]
	v_lshl_add_u64 v[200:201], v[188:189], 1, v[200:201]
	s_ashr_i32 s43, s42, 31
	s_waitcnt vmcnt(12)
	v_pk_add_f32 v[148:149], v[148:149], v[224:225]
	v_pk_add_f32 v[154:155], v[154:155], v[230:231]
	v_pk_add_f32 v[152:153], v[152:153], v[228:229]
	v_mul_f32_e32 v224, v155, v155
	v_mul_f32_e32 v223, v153, v153
	v_fmac_f32_e32 v223, v152, v152
	v_fmac_f32_e32 v224, v154, v154
	v_add_f32_e32 v223, v223, v224
	v_mul_f32_e32 v224, v149, v149
	v_pk_add_f32 v[126:127], v[126:127], v[246:247]
	v_pk_add_f32 v[124:125], v[124:125], v[244:245]
	v_pk_add_f32 v[150:151], v[150:151], v[226:227]
	global_store_dwordx4 v[198:199], v[152:155], off
	global_store_dwordx4 v[198:199], v[148:151], off offset:16
	v_fmac_f32_e32 v224, v148, v148
	v_cvt_pk_bf16_f32 v152, v152, v153
	v_cvt_pk_bf16_f32 v153, v154, v155
	v_cvt_pk_bf16_f32 v154, v148, v149
	v_pk_add_f32 v[120:121], v[120:121], v[232:233]
	v_mul_f32_e32 v148, v125, v125
	v_mul_f32_e32 v149, v127, v127
	v_fmac_f32_e32 v148, v124, v124
	v_fmac_f32_e32 v149, v126, v126
	v_add_f32_e32 v148, v148, v149
	v_mul_f32_e32 v149, v121, v121
	v_cvt_pk_bf16_f32 v155, v150, v151
	global_store_dwordx4 v[200:201], v[152:155], off
	v_pk_add_f32 v[122:123], v[122:123], v[234:235]
	global_store_dwordx4 v[198:199], v[124:127], off offset:512
	global_store_dwordx4 v[198:199], v[120:123], off offset:528
	v_fmac_f32_e32 v149, v120, v120
	v_cvt_pk_bf16_f32 v124, v124, v125
	v_cvt_pk_bf16_f32 v125, v126, v127
	v_cvt_pk_bf16_f32 v126, v120, v121
	v_add_f32_e32 v223, v223, v224
	v_and_b32_e32 v121, 64, v239
	v_mul_f32_e32 v224, v151, v151
	v_add_f32_e32 v148, v148, v149
	v_mul_f32_e32 v149, v123, v123
	v_xor_b32_e32 v120, 16, v239
	v_add_u32_e32 v121, 64, v121
	v_fmac_f32_e32 v224, v150, v150
	v_fmac_f32_e32 v149, v122, v122
	v_cmp_lt_i32_e32 vcc, v120, v121
	v_add_f32_e32 v223, v224, v223
	v_add_f32_e32 v148, v149, v148
	v_cndmask_b32_e32 v120, v239, v120, vcc
	v_add_f32_e32 v148, v223, v148
	v_cvt_pk_bf16_f32 v127, v122, v123
	global_store_dwordx4 v[200:201], v[124:127], off offset:256
	v_xor_b32_e32 v122, 32, v239
	v_cmp_lt_i32_e32 vcc, v122, v121
	v_lshlrev_b32_e32 v126, 2, v120
	ds_bpermute_b32 v120, v126, v148
	v_cndmask_b32_e32 v121, v239, v122, vcc
	v_lshlrev_b32_e32 v127, 2, v121
	s_waitcnt lgkmcnt(0)
	v_add_f32_e32 v120, v148, v120
	ds_bpermute_b32 v121, v127, v120
	s_and_saveexec_b64 s[46:47], s[38:39]
	s_cbranch_execz .LBB0_730
	v_lshlrev_b64 v[122:123], 7, v[190:191]
	v_lshl_add_u64 v[122:123], s[94:95], 0, v[122:123]
	v_lshl_add_u64 v[122:123], s[42:43], 2, v[122:123]
	s_lshl_b32 s30, s57, 2
	v_lshl_add_u64 v[122:123], v[122:123], 0, s[30:31]
	s_waitcnt lgkmcnt(0)
	v_add_f32_e32 v120, v120, v121
	global_store_dword v[122:123], v120, off

; #define PG8_STAGE(bufoff, gbase, voff) do { _Pragma("unroll") for (int _i = 0; _i < 2; ++_i) \
;         __builtin_amdgcn_global_load_lds((const unsigned*)((const char*)(gbase) + (voff)[_i]), (LAS unsigned*)(lds + (bufoff) + ldsw + _i * 8192), 16, 0, 0); } while (0)
; #define PG8_LDA(dst, b, h) do { _Pragma("unroll") for (int m = 0; m < 4; ++m) _Pragma("unroll") for (int k = 0; k < 2; ++k) dst[m][k] = *(const LAS bf16x8*)(lds + PG8_SA(b, h) + aoff + m * 2048 + k * 1024); } while (0)
; #define PG8_LDB(dst, b, h) do { _Pragma("unroll") for (int n = 0; n < 2; ++n) _Pragma("unroll") for (int k = 0; k < 2; ++k) dst[n][k] = *(const LAS bf16x8*)(lds + PG8_SB(b, h) + boff + n * 2048 + k * 1024); } while (0)
; #define PG8_MMA(ai, bj, At, Bt) do { __builtin_amdgcn_s_setprio(1); _Pragma("unroll") for (int m = 0; m < 4; ++m) _Pragma("unroll") for (int n = 0; n < 2; ++n) _Pragma("unroll") for (int k = 0; k < 2; ++k) \
;         acc[ai][bj][m][n] = __builtin_amdgcn_mfma_f32_16x16x32_bf16(Bt[n][k], At[m][k], acc[ai][bj][m][n], 0, 0, 0); __builtin_amdgcn_s_setprio(0); } while (0)
; #define PG8_WAIT_V(n) asm volatile("s_waitcnt vmcnt(" #n ")" ::: "memory")
; #define PG8_WAIT_L(n) asm volatile("s_waitcnt lgkmcnt(" #n ")" ::: "memory")
; #define PG8_BAR __builtin_amdgcn_s_barrier()
; #define PG8_SCHED __builtin_amdgcn_sched_barrier(0)
; template <class Epi, bool ALIGN_EPI>
; __device__ __forceinline__ void gemm_phase(LAS unsigned char* lds, const Gemm g, int G, int cid, const Epi& E) {
;     ...
;             const char* a1 = cA + (size_t)(t + 1) * kA;
;             const char* a2 = last ? nA : cA + (size_t)(t + 2) * kA; const char* b2 = last ? nB : cB + (size_t)(t + 2) * kB;
;             const char* a3 = a2 + kA; const char* b3 = b2 + kB;
;             PG8_LDB(B0, 0, 0); PG8_LDB(B1, 0, 1); PG8_SCHED; PG8_LDA(At, 0, 0); PG8_STAGE(PG8_SA(1, 1), a1 + hA, voffA);
;             PG8_WAIT_V(8); PG8_WAIT_L(0); PG8_BAR; PG8_MMA(0, 0, At, B0); PG8_MMA(0, 1, At, B1); PG8_BAR; PG8_SCHED;
;             PG8_LDA(At, 0, 1); PG8_STAGE(PG8_SB(0, 0), b2, voffB); PG8_STAGE(PG8_SB(0, 1), b2 + hB, voffB); PG8_STAGE(PG8_SA(0, 0), a2, voffA);
;             PG8_WAIT_V(8); PG8_WAIT_L(0); PG8_BAR; PG8_MMA(1, 0, At, B0); PG8_MMA(1, 1, At, B1); PG8_BAR; PG8_SCHED;
.LBB0_813:
	s_add_u32 s54, s52, 0x100
	s_addc_u32 s55, s53, 0
	s_and_b64 s[6:7], exec, s[58:59]
	s_cselect_b32 s59, s45, s55
	s_cselect_b32 s58, s44, s54
	s_add_i32 s6, 0, 0x10000
	s_add_i32 s92, 0, 0x14000
	v_add_u32_e32 v144, s6, v176
	v_add_u32_e32 v160, s92, v176
	ds_read_b128 v[128:131], v144
	ds_read_b128 v[132:135], v144 offset:1024
	ds_read_b128 v[140:143], v144 offset:2048
	ds_read_b128 v[144:147], v144 offset:3072
	ds_read_b128 v[148:151], v160
	ds_read_b128 v[152:155], v160 offset:1024
	ds_read_b128 v[156:159], v160 offset:2048
	ds_read_b128 v[160:163], v160 offset:3072
	v_lshl_add_u64 v[198:199], s[52:53], 0, v[170:171]
	s_add_i32 m0, s13, 0xc000
	ds_read_b128 v[180:183], v179
	ds_read_b128 v[184:187], v179 offset:1024
	ds_read_b128 v[188:191], v179 offset:2048
	ds_read_b128 v[206:209], v179 offset:3072
	ds_read_b128 v[210:213], v179 offset:4096
	ds_read_b128 v[214:217], v179 offset:5120
	ds_read_b128 v[218:221], v179 offset:6144
	ds_read_b128 v[222:225], v179 offset:7168
	global_load_lds_dwordx4 v[198:199], off
	v_lshl_add_u64 v[198:199], s[52:53], 0, v[172:173]
	s_add_i32 m0, s13, 0xe000
	s_nop 0
	global_load_lds_dwordx4 v[198:199], off
	s_waitcnt vmcnt(8)
	s_waitcnt lgkmcnt(0)
	s_barrier
	s_waitcnt lgkmcnt(0)
	v_mfma_f32_16x16x32_bf16 v[124:127], v[128:131], v[180:183], v[124:127]
	v_mfma_f32_16x16x32_bf16 v[120:123], v[140:143], v[180:183], v[120:123]
	v_mfma_f32_16x16x32_bf16 v[108:111], v[128:131], v[188:191], v[108:111]
	v_mfma_f32_16x16x32_bf16 v[104:107], v[140:143], v[188:191], v[104:107]
	v_mfma_f32_16x16x32_bf16 v[92:95], v[128:131], v[210:213], v[92:95]
	v_mfma_f32_16x16x32_bf16 v[88:91], v[140:143], v[210:213], v[88:91]
	v_mfma_f32_16x16x32_bf16 v[76:79], v[128:131], v[218:221], v[76:79]
	v_mfma_f32_16x16x32_bf16 v[72:75], v[140:143], v[218:221], v[72:75]
	v_mfma_f32_16x16x32_bf16 v[124:127], v[132:135], v[184:187], v[124:127]
	v_mfma_f32_16x16x32_bf16 v[120:123], v[144:147], v[184:187], v[120:123]
	v_mfma_f32_16x16x32_bf16 v[108:111], v[132:135], v[206:209], v[108:111]
	v_mfma_f32_16x16x32_bf16 v[104:107], v[144:147], v[206:209], v[104:107]
	v_mfma_f32_16x16x32_bf16 v[92:95], v[132:135], v[214:217], v[92:95]
	v_mfma_f32_16x16x32_bf16 v[88:91], v[144:147], v[214:217], v[88:91]
	v_mfma_f32_16x16x32_bf16 v[76:79], v[132:135], v[222:225], v[76:79]
	v_mfma_f32_16x16x32_bf16 v[72:75], v[144:147], v[222:225], v[72:75]
	v_mfma_f32_16x16x32_bf16 v[116:119], v[148:151], v[180:183], v[116:119]
	v_mfma_f32_16x16x32_bf16 v[112:115], v[156:159], v[180:183], v[112:115]
	v_mfma_f32_16x16x32_bf16 v[100:103], v[148:151], v[188:191], v[100:103]
	v_mfma_f32_16x16x32_bf16 v[96:99], v[156:159], v[188:191], v[96:99]
	v_mfma_f32_16x16x32_bf16 v[84:87], v[148:151], v[210:213], v[84:87]
	v_mfma_f32_16x16x32_bf16 v[80:83], v[156:159], v[210:213], v[80:83]
	v_mfma_f32_16x16x32_bf16 v[68:71], v[148:151], v[218:221], v[68:71]
	v_mfma_f32_16x16x32_bf16 v[64:67], v[156:159], v[218:221], v[64:67]
	v_mfma_f32_16x16x32_bf16 v[116:119], v[152:155], v[184:187], v[116:119]
	v_mfma_f32_16x16x32_bf16 v[112:115], v[160:163], v[184:187], v[112:115]
	v_mfma_f32_16x16x32_bf16 v[100:103], v[152:155], v[206:209], v[100:103]
	v_mfma_f32_16x16x32_bf16 v[96:99], v[160:163], v[206:209], v[96:99]
	v_mfma_f32_16x16x32_bf16 v[84:87], v[152:155], v[214:217], v[84:87]
	v_mfma_f32_16x16x32_bf16 v[80:83], v[160:163], v[214:217], v[80:83]
	v_mfma_f32_16x16x32_bf16 v[68:71], v[152:155], v[222:225], v[68:71]
	v_mfma_f32_16x16x32_bf16 v[64:67], v[160:163], v[222:225], v[64:67]
	s_barrier
	s_add_i32 s6, s6, s12
	v_lshl_add_u64 v[198:199], s[56:57], 0, v[164:165]
	s_mov_b32 m0, s6
	ds_read_b128 v[180:183], v179 offset:16384
	ds_read_b128 v[184:187], v179 offset:17408
	ds_read_b128 v[188:191], v179 offset:18432
	ds_read_b128 v[206:209], v179 offset:19456
	ds_read_b128 v[210:213], v179 offset:20480
	ds_read_b128 v[214:217], v179 offset:21504
	ds_read_b128 v[218:221], v179 offset:22528
	ds_read_b128 v[222:225], v179 offset:23552
	global_load_lds_dwordx4 v[198:199], off
	s_add_i32 m0, s6, 0x2000
	s_add_u32 s6, s56, 0x2000
	v_lshl_add_u64 v[198:199], s[56:57], 0, v[168:169]
	s_addc_u32 s7, s57, 0
	s_add_i32 s52, s92, s12
	global_load_lds_dwordx4 v[198:199], off
	v_lshl_add_u64 v[198:199], s[6:7], 0, v[164:165]
	s_mov_b32 m0, s52
	v_lshl_add_u64 v[200:201], s[58:59], 0, v[166:167]
	global_load_lds_dwordx4 v[198:199], off
	v_lshl_add_u64 v[198:199], s[6:7], 0, v[168:169]
	s_add_i32 m0, s52, 0x2000
	s_nop 0
	global_load_lds_dwordx4 v[198:199], off
	v_lshl_add_u64 v[198:199], s[58:59], 0, v[136:137]
	s_mov_b32 m0, s13
	s_nop 0
	global_load_lds_dwordx4 v[198:199], off
	s_mov_b32 m0, s24
	s_nop 0
	global_load_lds_dwordx4 v[200:201], off
	s_waitcnt vmcnt(8)
	s_waitcnt lgkmcnt(0)
	s_barrier
; #define PG8_STAGE(bufoff, gbase, voff) do { _Pragma("unroll") for (int _i = 0; _i < 2; ++_i) \
;         __builtin_amdgcn_global_load_lds((const unsigned*)((const char*)(gbase) + (voff)[_i]), (LAS unsigned*)(lds + (bufoff) + ldsw + _i * 8192), 16, 0, 0); } while (0)
; #define PG8_LDA(dst, b, h) do { _Pragma("unroll") for (int m = 0; m < 4; ++m) _Pragma("unroll") for (int k = 0; k < 2; ++k) dst[m][k] = *(const LAS bf16x8*)(lds + PG8_SA(b, h) + aoff + m * 2048 + k * 1024); } while (0)
; #define PG8_LDB(dst, b, h) do { _Pragma("unroll") for (int n = 0; n < 2; ++n) _Pragma("unroll") for (int k = 0; k < 2; ++k) dst[n][k] = *(const LAS bf16x8*)(lds + PG8_SB(b, h) + boff + n * 2048 + k * 1024); } while (0)
; #define PG8_MMA(ai, bj, At, Bt) do { __builtin_amdgcn_s_setprio(1); _Pragma("unroll") for (int m = 0; m < 4; ++m) _Pragma("unroll") for (int n = 0; n < 2; ++n) _Pragma("unroll") for (int k = 0; k < 2; ++k) \
;         acc[ai][bj][m][n] = __builtin_amdgcn_mfma_f32_16x16x32_bf16(Bt[n][k], At[m][k], acc[ai][bj][m][n], 0, 0, 0); __builtin_amdgcn_s_setprio(0); } while (0)
; #define PG8_WAIT_V(n) asm volatile("s_waitcnt vmcnt(" #n ")" ::: "memory")
; #define PG8_WAIT_L(n) asm volatile("s_waitcnt lgkmcnt(" #n ")" ::: "memory")
; #define PG8_BAR __builtin_amdgcn_s_barrier()
; #define PG8_SCHED __builtin_amdgcn_sched_barrier(0)
; template <class Epi, bool ALIGN_EPI>
; __device__ __forceinline__ void gemm_phase(LAS unsigned char* lds, const Gemm g, int G, int cid, const Epi& E) {
;     ...
;             PG8_WAIT_V(8); PG8_WAIT_L(0); PG8_BAR; PG8_MMA(1, 0, At, B0); PG8_MMA(1, 1, At, B1); PG8_BAR; PG8_SCHED;
;             PG8_LDB(B0, 1, 0); PG8_LDB(B1, 1, 1); PG8_SCHED; PG8_LDA(At, 1, 0); PG8_STAGE(PG8_SA(0, 1), a2 + hA, voffA);
;             PG8_WAIT_V(8); PG8_WAIT_L(0); PG8_BAR; PG8_MMA(0, 0, At, B0); PG8_MMA(0, 1, At, B1); PG8_BAR; PG8_SCHED;
	s_waitcnt lgkmcnt(0)
	v_mfma_f32_16x16x32_bf16 v[60:63], v[128:131], v[180:183], v[60:63]
	v_mfma_f32_16x16x32_bf16 v[56:59], v[140:143], v[180:183], v[56:59]
	v_mfma_f32_16x16x32_bf16 v[44:47], v[128:131], v[188:191], v[44:47]
	v_mfma_f32_16x16x32_bf16 v[40:43], v[140:143], v[188:191], v[40:43]
	v_mfma_f32_16x16x32_bf16 v[28:31], v[128:131], v[210:213], v[28:31]
	v_mfma_f32_16x16x32_bf16 v[24:27], v[140:143], v[210:213], v[24:27]
	v_mfma_f32_16x16x32_bf16 v[12:15], v[128:131], v[218:221], v[12:15]
	v_mfma_f32_16x16x32_bf16 v[8:11], v[140:143], v[218:221], v[8:11]
	v_mfma_f32_16x16x32_bf16 v[60:63], v[132:135], v[184:187], v[60:63]
	v_mfma_f32_16x16x32_bf16 v[56:59], v[144:147], v[184:187], v[56:59]
	v_mfma_f32_16x16x32_bf16 v[44:47], v[132:135], v[206:209], v[44:47]
	v_mfma_f32_16x16x32_bf16 v[40:43], v[144:147], v[206:209], v[40:43]
	v_mfma_f32_16x16x32_bf16 v[28:31], v[132:135], v[214:217], v[28:31]
	v_mfma_f32_16x16x32_bf16 v[24:27], v[144:147], v[214:217], v[24:27]
	v_mfma_f32_16x16x32_bf16 v[12:15], v[132:135], v[222:225], v[12:15]
	v_mfma_f32_16x16x32_bf16 v[8:11], v[144:147], v[222:225], v[8:11]
	v_mfma_f32_16x16x32_bf16 v[52:55], v[148:151], v[180:183], v[52:55]
	v_mfma_f32_16x16x32_bf16 v[48:51], v[156:159], v[180:183], v[48:51]
	v_mfma_f32_16x16x32_bf16 v[36:39], v[148:151], v[188:191], v[36:39]
	v_mfma_f32_16x16x32_bf16 v[32:35], v[156:159], v[188:191], v[32:35]
	v_mfma_f32_16x16x32_bf16 v[20:23], v[148:151], v[210:213], v[20:23]
	v_mfma_f32_16x16x32_bf16 v[16:19], v[156:159], v[210:213], v[16:19]
	v_mfma_f32_16x16x32_bf16 v[4:7], v[148:151], v[218:221], v[4:7]
	v_mfma_f32_16x16x32_bf16 v[0:3], v[156:159], v[218:221], v[0:3]
	v_mfma_f32_16x16x32_bf16 v[52:55], v[152:155], v[184:187], v[52:55]
	v_mfma_f32_16x16x32_bf16 v[48:51], v[160:163], v[184:187], v[48:51]
	v_mfma_f32_16x16x32_bf16 v[36:39], v[152:155], v[206:209], v[36:39]
	v_mfma_f32_16x16x32_bf16 v[32:35], v[160:163], v[206:209], v[32:35]
	v_mfma_f32_16x16x32_bf16 v[20:23], v[152:155], v[214:217], v[20:23]
	v_mfma_f32_16x16x32_bf16 v[16:19], v[160:163], v[214:217], v[16:19]
	v_mfma_f32_16x16x32_bf16 v[4:7], v[152:155], v[222:225], v[4:7]
	v_mfma_f32_16x16x32_bf16 v[0:3], v[160:163], v[222:225], v[0:3]
	s_barrier
	s_add_i32 s52, 0, 0x18000
	s_add_i32 s53, 0, 0x1c000
	v_add_u32_e32 v144, s52, v176
	v_add_u32_e32 v160, s53, v176
	ds_read_b128 v[128:131], v144
	ds_read_b128 v[132:135], v144 offset:1024
	ds_read_b128 v[140:143], v144 offset:2048
	ds_read_b128 v[144:147], v144 offset:3072
	ds_read_b128 v[148:151], v160
	ds_read_b128 v[152:155], v160 offset:1024
	ds_read_b128 v[156:159], v160 offset:2048
	ds_read_b128 v[160:163], v160 offset:3072
	s_add_u32 s6, s58, 0x84000
	s_addc_u32 s7, s59, 0
	s_mov_b32 m0, s25
	v_lshl_add_u64 v[226:227], s[6:7], 0, v[136:137]
	ds_read_b128 v[180:183], v179 offset:32768
	ds_read_b128 v[184:187], v179 offset:33792
	ds_read_b128 v[188:191], v179 offset:34816
	ds_read_b128 v[206:209], v179 offset:35840
	ds_read_b128 v[210:213], v179 offset:36864
	ds_read_b128 v[214:217], v179 offset:37888
	ds_read_b128 v[218:221], v179 offset:38912
	ds_read_b128 v[222:225], v179 offset:39936
	global_load_lds_dwordx4 v[226:227], off
	v_lshl_add_u64 v[226:227], s[6:7], 0, v[166:167]
	s_mov_b32 m0, s74
	s_nop 0
	global_load_lds_dwordx4 v[226:227], off
	s_waitcnt vmcnt(8)
	s_waitcnt lgkmcnt(0)
	s_barrier
	s_waitcnt lgkmcnt(0)
	v_mfma_f32_16x16x32_bf16 v[124:127], v[128:131], v[180:183], v[124:127]
	v_mfma_f32_16x16x32_bf16 v[120:123], v[140:143], v[180:183], v[120:123]
	v_mfma_f32_16x16x32_bf16 v[108:111], v[128:131], v[188:191], v[108:111]
	v_mfma_f32_16x16x32_bf16 v[104:107], v[140:143], v[188:191], v[104:107]
	v_mfma_f32_16x16x32_bf16 v[92:95], v[128:131], v[210:213], v[92:95]
	v_mfma_f32_16x16x32_bf16 v[88:91], v[140:143], v[210:213], v[88:91]
	v_mfma_f32_16x16x32_bf16 v[76:79], v[128:131], v[218:221], v[76:79]
	v_mfma_f32_16x16x32_bf16 v[72:75], v[140:143], v[218:221], v[72:75]
	v_mfma_f32_16x16x32_bf16 v[124:127], v[132:135], v[184:187], v[124:127]
	v_mfma_f32_16x16x32_bf16 v[120:123], v[144:147], v[184:187], v[120:123]
	v_mfma_f32_16x16x32_bf16 v[108:111], v[132:135], v[206:209], v[108:111]
	v_mfma_f32_16x16x32_bf16 v[104:107], v[144:147], v[206:209], v[104:107]
	v_mfma_f32_16x16x32_bf16 v[92:95], v[132:135], v[214:217], v[92:95]
	v_mfma_f32_16x16x32_bf16 v[88:91], v[144:147], v[214:217], v[88:91]
	v_mfma_f32_16x16x32_bf16 v[76:79], v[132:135], v[222:225], v[76:79]
	v_mfma_f32_16x16x32_bf16 v[72:75], v[144:147], v[222:225], v[72:75]
	v_mfma_f32_16x16x32_bf16 v[116:119], v[148:151], v[180:183], v[116:119]
	v_mfma_f32_16x16x32_bf16 v[112:115], v[156:159], v[180:183], v[112:115]
	v_mfma_f32_16x16x32_bf16 v[100:103], v[148:151], v[188:191], v[100:103]
	v_mfma_f32_16x16x32_bf16 v[96:99], v[156:159], v[188:191], v[96:99]
	v_mfma_f32_16x16x32_bf16 v[84:87], v[148:151], v[210:213], v[84:87]
	v_mfma_f32_16x16x32_bf16 v[80:83], v[156:159], v[210:213], v[80:83]
	v_mfma_f32_16x16x32_bf16 v[68:71], v[148:151], v[218:221], v[68:71]
	v_mfma_f32_16x16x32_bf16 v[64:67], v[156:159], v[218:221], v[64:67]
	v_mfma_f32_16x16x32_bf16 v[116:119], v[152:155], v[184:187], v[116:119]
	v_mfma_f32_16x16x32_bf16 v[112:115], v[160:163], v[184:187], v[112:115]
	v_mfma_f32_16x16x32_bf16 v[100:103], v[152:155], v[206:209], v[100:103]
	v_mfma_f32_16x16x32_bf16 v[96:99], v[160:163], v[206:209], v[96:99]
	v_mfma_f32_16x16x32_bf16 v[84:87], v[152:155], v[214:217], v[84:87]
	v_mfma_f32_16x16x32_bf16 v[80:83], v[160:163], v[214:217], v[80:83]
	v_mfma_f32_16x16x32_bf16 v[68:71], v[152:155], v[222:225], v[68:71]
	v_mfma_f32_16x16x32_bf16 v[64:67], v[160:163], v[222:225], v[64:67]
	s_barrier
; #define PG8_STAGE(bufoff, gbase, voff) do { _Pragma("unroll") for (int _i = 0; _i < 2; ++_i) \
;         __builtin_amdgcn_global_load_lds((const unsigned*)((const char*)(gbase) + (voff)[_i]), (LAS unsigned*)(lds + (bufoff) + ldsw + _i * 8192), 16, 0, 0); } while (0)
; #define PG8_LDA(dst, b, h) do { _Pragma("unroll") for (int m = 0; m < 4; ++m) _Pragma("unroll") for (int k = 0; k < 2; ++k) dst[m][k] = *(const LAS bf16x8*)(lds + PG8_SA(b, h) + aoff + m * 2048 + k * 1024); } while (0)
; #define PG8_MMA(ai, bj, At, Bt) do { __builtin_amdgcn_s_setprio(1); _Pragma("unroll") for (int m = 0; m < 4; ++m) _Pragma("unroll") for (int n = 0; n < 2; ++n) _Pragma("unroll") for (int k = 0; k < 2; ++k) \
;         acc[ai][bj][m][n] = __builtin_amdgcn_mfma_f32_16x16x32_bf16(Bt[n][k], At[m][k], acc[ai][bj][m][n], 0, 0, 0); __builtin_amdgcn_s_setprio(0); } while (0)
; #define PG8_WAIT_V(n) asm volatile("s_waitcnt vmcnt(" #n ")" ::: "memory")
; #define PG8_WAIT_L(n) asm volatile("s_waitcnt lgkmcnt(" #n ")" ::: "memory")
; #define PG8_BAR __builtin_amdgcn_s_barrier()
; #define PG8_SCHED __builtin_amdgcn_sched_barrier(0)
; template <class Epi, bool ALIGN_EPI>
; __device__ __forceinline__ void gemm_phase(LAS unsigned char* lds, const Gemm g, int G, int cid, const Epi& E) {
;     ...
;             PG8_LDA(At, 1, 1); PG8_STAGE(PG8_SB(1, 0), b3, voffB); PG8_STAGE(PG8_SB(1, 1), b3 + hB, voffB); PG8_STAGE(PG8_SA(1, 0), a3, voffA);
;             PG8_WAIT_V(8); PG8_WAIT_L(0); PG8_BAR; PG8_MMA(1, 0, At, B0); PG8_MMA(1, 1, At, B1); PG8_BAR; PG8_SCHED;
	s_add_u32 s6, s56, 0x160000
	s_addc_u32 s7, s57, 0
	s_add_i32 s52, s52, s12
	v_lshl_add_u64 v[226:227], s[6:7], 0, v[164:165]
	s_mov_b32 m0, s52
	ds_read_b128 v[180:183], v179 offset:49152
	ds_read_b128 v[184:187], v179 offset:50176
	ds_read_b128 v[188:191], v179 offset:51200
	ds_read_b128 v[206:209], v179 offset:52224
	ds_read_b128 v[210:213], v179 offset:53248
	ds_read_b128 v[214:217], v179 offset:54272
	ds_read_b128 v[218:221], v179 offset:55296
	ds_read_b128 v[222:225], v179 offset:56320
	global_load_lds_dwordx4 v[226:227], off
	s_add_i32 m0, s52, 0x2000
	v_lshl_add_u64 v[226:227], s[6:7], 0, v[168:169]
	s_add_u32 s6, s56, 0x162000
	s_addc_u32 s7, s57, 0
	s_add_i32 s52, s53, s12
	global_load_lds_dwordx4 v[226:227], off
	v_lshl_add_u64 v[226:227], s[6:7], 0, v[164:165]
	s_mov_b32 m0, s52
	v_lshl_add_u64 v[198:199], v[198:199], 0, s[36:37]
	global_load_lds_dwordx4 v[226:227], off
	v_lshl_add_u64 v[226:227], s[6:7], 0, v[168:169]
	s_add_i32 m0, s52, 0x2000
	s_nop 0
	global_load_lds_dwordx4 v[226:227], off
	s_mov_b32 m0, s75
	s_nop 0
	global_load_lds_dwordx4 v[198:199], off
	v_lshl_add_u64 v[198:199], v[200:201], 0, s[36:37]
	s_mov_b32 m0, s76
	s_nop 0
	global_load_lds_dwordx4 v[198:199], off
	s_waitcnt vmcnt(8)
	s_waitcnt lgkmcnt(0)
	s_barrier
	s_waitcnt lgkmcnt(0)
	v_mfma_f32_16x16x32_bf16 v[60:63], v[128:131], v[180:183], v[60:63]
	v_mfma_f32_16x16x32_bf16 v[56:59], v[140:143], v[180:183], v[56:59]
	v_mfma_f32_16x16x32_bf16 v[44:47], v[128:131], v[188:191], v[44:47]
	v_mfma_f32_16x16x32_bf16 v[40:43], v[140:143], v[188:191], v[40:43]
	v_mfma_f32_16x16x32_bf16 v[28:31], v[128:131], v[210:213], v[28:31]
	v_mfma_f32_16x16x32_bf16 v[24:27], v[140:143], v[210:213], v[24:27]
	v_mfma_f32_16x16x32_bf16 v[12:15], v[128:131], v[218:221], v[12:15]
	v_mfma_f32_16x16x32_bf16 v[8:11], v[140:143], v[218:221], v[8:11]
	v_mfma_f32_16x16x32_bf16 v[60:63], v[132:135], v[184:187], v[60:63]
	v_mfma_f32_16x16x32_bf16 v[56:59], v[144:147], v[184:187], v[56:59]
	v_mfma_f32_16x16x32_bf16 v[44:47], v[132:135], v[206:209], v[44:47]
	v_mfma_f32_16x16x32_bf16 v[40:43], v[144:147], v[206:209], v[40:43]
	v_mfma_f32_16x16x32_bf16 v[28:31], v[132:135], v[214:217], v[28:31]
	v_mfma_f32_16x16x32_bf16 v[24:27], v[144:147], v[214:217], v[24:27]
	v_mfma_f32_16x16x32_bf16 v[12:15], v[132:135], v[222:225], v[12:15]
	v_mfma_f32_16x16x32_bf16 v[8:11], v[144:147], v[222:225], v[8:11]
	v_mfma_f32_16x16x32_bf16 v[52:55], v[148:151], v[180:183], v[52:55]
	v_mfma_f32_16x16x32_bf16 v[48:51], v[156:159], v[180:183], v[48:51]
	v_mfma_f32_16x16x32_bf16 v[36:39], v[148:151], v[188:191], v[36:39]
	v_mfma_f32_16x16x32_bf16 v[32:35], v[156:159], v[188:191], v[32:35]
	v_mfma_f32_16x16x32_bf16 v[20:23], v[148:151], v[210:213], v[20:23]
	v_mfma_f32_16x16x32_bf16 v[16:19], v[156:159], v[210:213], v[16:19]
	v_mfma_f32_16x16x32_bf16 v[4:7], v[148:151], v[218:221], v[4:7]
	v_mfma_f32_16x16x32_bf16 v[0:3], v[156:159], v[218:221], v[0:3]
	v_mfma_f32_16x16x32_bf16 v[52:55], v[152:155], v[184:187], v[52:55]
	v_mfma_f32_16x16x32_bf16 v[48:51], v[160:163], v[184:187], v[48:51]
	v_mfma_f32_16x16x32_bf16 v[36:39], v[152:155], v[206:209], v[36:39]
	v_mfma_f32_16x16x32_bf16 v[32:35], v[160:163], v[206:209], v[32:35]
	v_mfma_f32_16x16x32_bf16 v[20:23], v[152:155], v[214:217], v[20:23]
	v_mfma_f32_16x16x32_bf16 v[16:19], v[160:163], v[214:217], v[16:19]
	v_mfma_f32_16x16x32_bf16 v[4:7], v[152:155], v[222:225], v[4:7]
	v_mfma_f32_16x16x32_bf16 v[0:3], v[160:163], v[222:225], v[0:3]
	s_barrier
	s_add_i32 s91, s91, 2
	s_add_u32 s50, s50, 0x2c0000
	s_addc_u32 s51, s51, 0
	s_cmp_gt_u32 s91, 29
	s_mov_b64 s[52:53], s[54:55]
	s_cbranch_scc1 .LBB0_816

; #define PG8_STAGE(bufoff, gbase, voff) do { _Pragma("unroll") for (int _i = 0; _i < 2; ++_i) \
;         __builtin_amdgcn_global_load_lds((const unsigned*)((const char*)(gbase) + (voff)[_i]), (LAS unsigned*)(lds + (bufoff) + ldsw + _i * 8192), 16, 0, 0); } while (0)
; #define PG8_LDA(dst, b, h) do { _Pragma("unroll") for (int m = 0; m < 4; ++m) _Pragma("unroll") for (int k = 0; k < 2; ++k) dst[m][k] = *(const LAS bf16x8*)(lds + PG8_SA(b, h) + aoff + m * 2048 + k * 1024); } while (0)
; #define PG8_LDB(dst, b, h) do { _Pragma("unroll") for (int n = 0; n < 2; ++n) _Pragma("unroll") for (int k = 0; k < 2; ++k) dst[n][k] = *(const LAS bf16x8*)(lds + PG8_SB(b, h) + boff + n * 2048 + k * 1024); } while (0)
; #define PG8_MMA(ai, bj, At, Bt) do { __builtin_amdgcn_s_setprio(1); _Pragma("unroll") for (int m = 0; m < 4; ++m) _Pragma("unroll") for (int n = 0; n < 2; ++n) _Pragma("unroll") for (int k = 0; k < 2; ++k) \
;         acc[ai][bj][m][n] = __builtin_amdgcn_mfma_f32_16x16x32_bf16(Bt[n][k], At[m][k], acc[ai][bj][m][n], 0, 0, 0); __builtin_amdgcn_s_setprio(0); } while (0)
; #define PG8_WAIT_V(n) asm volatile("s_waitcnt vmcnt(" #n ")" ::: "memory")
; #define PG8_WAIT_L(n) asm volatile("s_waitcnt lgkmcnt(" #n ")" ::: "memory")
; #define PG8_BAR __builtin_amdgcn_s_barrier()
; template <class Epi, bool ALIGN_EPI>
; __device__ __forceinline__ void gemm_phase(LAS unsigned char* lds, const Gemm g, int G, int cid, const Epi& E) {
;     ...
;         const char* nA = has_next ? tileA(g, nxt) : cA; const char* nB = has_next ? tileB(g, nxt) : cB;
;         for (int t = 0; t < nt; t += 2) {
;             const bool last = (t == nt - 2);
;             const char* a1 = cA + (size_t)(t + 1) * kA;
;             const char* a2 = last ? nA : cA + (size_t)(t + 2) * kA; const char* b2 = last ? nB : cB + (size_t)(t + 2) * kB;
;             const char* a3 = a2 + kA; const char* b3 = b2 + kB;
;             PG8_LDB(B0, 0, 0); PG8_LDB(B1, 0, 1); PG8_SCHED; PG8_LDA(At, 0, 0); PG8_STAGE(PG8_SA(1, 1), a1 + hA, voffA);
;             PG8_WAIT_V(8); PG8_WAIT_L(0); PG8_BAR; PG8_MMA(0, 0, At, B0); PG8_MMA(0, 1, At, B1); PG8_BAR; PG8_SCHED;
;             PG8_LDA(At, 0, 1); PG8_STAGE(PG8_SB(0, 0), b2, voffB); PG8_STAGE(PG8_SB(0, 1), b2 + hB, voffB); PG8_STAGE(PG8_SA(0, 0), a2, voffA);
;             PG8_WAIT_V(8); PG8_WAIT_L(0); PG8_BAR; PG8_MMA(1, 0, At, B0); PG8_MMA(1, 1, At, B1); PG8_BAR; PG8_SCHED;
.LBB0_927:
	s_add_u32 s40, s48, 0x100
	s_addc_u32 s41, s49, 0
	s_add_i32 s6, 0, 0x10000
	s_cmpk_eq_i32 s79, 0x54
	s_cselect_b32 s53, s45, s41
	s_cselect_b32 s52, s44, s40
	s_cselect_b32 s51, s30, s78
	s_cselect_b32 s50, s76, s77
	s_add_i32 s86, 0, 0x14000
	v_add_u32_e32 v144, s6, v243
	v_add_u32_e32 v160, s86, v243
	ds_read_b128 v[128:131], v144
	ds_read_b128 v[132:135], v144 offset:1024
	ds_read_b128 v[140:143], v144 offset:2048
	ds_read_b128 v[144:147], v144 offset:3072
	ds_read_b128 v[148:151], v160
	ds_read_b128 v[152:155], v160 offset:1024
	ds_read_b128 v[156:159], v160 offset:2048
	ds_read_b128 v[160:163], v160 offset:3072
	v_lshl_add_u64 v[198:199], s[48:49], 0, v[210:211]
	s_add_i32 m0, s12, 0xc000
	ds_read_b128 v[164:167], v245
	ds_read_b128 v[168:171], v245 offset:1024
	ds_read_b128 v[172:175], v245 offset:2048
	ds_read_b128 v[176:179], v245 offset:3072
	ds_read_b128 v[180:183], v245 offset:4096
	ds_read_b128 v[184:187], v245 offset:5120
	ds_read_b128 v[188:191], v245 offset:6144
	ds_read_b128 v[214:217], v245 offset:7168
	global_load_lds_dwordx4 v[198:199], off
	v_lshl_add_u64 v[198:199], s[48:49], 0, v[212:213]
	s_add_i32 m0, s12, 0xe000
	s_nop 0
	global_load_lds_dwordx4 v[198:199], off
	s_add_i32 vcc_lo, s79, 2
	s_lshl_b32 vcc_lo, vcc_lo, 15
	s_and_b32 vcc_lo, vcc_lo, 0x1f0000
	s_lshl_b32 vcc_hi, s75, 21
	s_add_i32 vcc_lo, vcc_lo, vcc_hi
	s_lshl_b32 vcc_hi, s25, 3
	s_add_i32 vcc_lo, vcc_lo, vcc_hi
	s_lshl_b32 vcc_hi, s74, 10
	s_add_i32 vcc_lo, vcc_lo, vcc_hi
	s_add_u32 vcc_lo, s82, vcc_lo
	s_addc_u32 vcc_hi, s83, 0
	s_mov_b32 m0, 0x22c00
	s_nop 0
	global_load_lds_dwordx4 v226, vcc
	s_waitcnt vmcnt(9)
	s_waitcnt lgkmcnt(0)
	s_barrier
	s_waitcnt lgkmcnt(0)
	v_mfma_f32_16x16x32_bf16 v[124:127], v[128:131], v[164:167], v[124:127]
	v_mfma_f32_16x16x32_bf16 v[120:123], v[140:143], v[164:167], v[120:123]
	v_mfma_f32_16x16x32_bf16 v[108:111], v[128:131], v[172:175], v[108:111]
	v_mfma_f32_16x16x32_bf16 v[104:107], v[140:143], v[172:175], v[104:107]
	v_mfma_f32_16x16x32_bf16 v[92:95], v[128:131], v[180:183], v[92:95]
	v_mfma_f32_16x16x32_bf16 v[88:91], v[140:143], v[180:183], v[88:91]
	v_mfma_f32_16x16x32_bf16 v[76:79], v[128:131], v[188:191], v[76:79]
	v_mfma_f32_16x16x32_bf16 v[72:75], v[140:143], v[188:191], v[72:75]
	v_mfma_f32_16x16x32_bf16 v[124:127], v[132:135], v[168:171], v[124:127]
	v_mfma_f32_16x16x32_bf16 v[120:123], v[144:147], v[168:171], v[120:123]
	v_mfma_f32_16x16x32_bf16 v[108:111], v[132:135], v[176:179], v[108:111]
	v_mfma_f32_16x16x32_bf16 v[104:107], v[144:147], v[176:179], v[104:107]
	v_mfma_f32_16x16x32_bf16 v[92:95], v[132:135], v[184:187], v[92:95]
	v_mfma_f32_16x16x32_bf16 v[88:91], v[144:147], v[184:187], v[88:91]
	v_mfma_f32_16x16x32_bf16 v[76:79], v[132:135], v[214:217], v[76:79]
	v_mfma_f32_16x16x32_bf16 v[72:75], v[144:147], v[214:217], v[72:75]
	v_mfma_f32_16x16x32_bf16 v[116:119], v[148:151], v[164:167], v[116:119]
	v_mfma_f32_16x16x32_bf16 v[112:115], v[156:159], v[164:167], v[112:115]
	v_mfma_f32_16x16x32_bf16 v[100:103], v[148:151], v[172:175], v[100:103]
	v_mfma_f32_16x16x32_bf16 v[96:99], v[156:159], v[172:175], v[96:99]
	v_mfma_f32_16x16x32_bf16 v[84:87], v[148:151], v[180:183], v[84:87]
	v_mfma_f32_16x16x32_bf16 v[80:83], v[156:159], v[180:183], v[80:83]
	v_mfma_f32_16x16x32_bf16 v[68:71], v[148:151], v[188:191], v[68:71]
	v_mfma_f32_16x16x32_bf16 v[64:67], v[156:159], v[188:191], v[64:67]
	v_mfma_f32_16x16x32_bf16 v[116:119], v[152:155], v[168:171], v[116:119]
	v_mfma_f32_16x16x32_bf16 v[112:115], v[160:163], v[168:171], v[112:115]
	v_mfma_f32_16x16x32_bf16 v[100:103], v[152:155], v[176:179], v[100:103]
	v_mfma_f32_16x16x32_bf16 v[96:99], v[160:163], v[176:179], v[96:99]
	v_mfma_f32_16x16x32_bf16 v[84:87], v[152:155], v[184:187], v[84:87]
	v_mfma_f32_16x16x32_bf16 v[80:83], v[160:163], v[184:187], v[80:83]
	v_mfma_f32_16x16x32_bf16 v[68:71], v[152:155], v[214:217], v[68:71]
	v_mfma_f32_16x16x32_bf16 v[64:67], v[160:163], v[214:217], v[64:67]
	s_barrier
	s_add_i32 s6, s6, s25
	v_lshl_add_u64 v[198:199], s[50:51], 0, v[138:139]
	s_mov_b32 m0, s6
	ds_read_b128 v[164:167], v245 offset:16384
	ds_read_b128 v[168:171], v245 offset:17408
	ds_read_b128 v[172:175], v245 offset:18432
	ds_read_b128 v[176:179], v245 offset:19456
	ds_read_b128 v[180:183], v245 offset:20480
	ds_read_b128 v[184:187], v245 offset:21504
	ds_read_b128 v[188:191], v245 offset:22528
	ds_read_b128 v[214:217], v245 offset:23552
	global_load_lds_dwordx4 v[198:199], off
	s_add_i32 m0, s6, 0x2000
	s_add_u32 s6, s50, 0x2000
	v_lshl_add_u64 v[198:199], s[50:51], 0, v[136:137]
	s_addc_u32 s7, s51, 0
	s_add_i32 s48, s86, s25
	global_load_lds_dwordx4 v[198:199], off
	v_lshl_add_u64 v[198:199], s[6:7], 0, v[138:139]
	s_mov_b32 m0, s48
	v_lshl_add_u64 v[200:201], s[52:53], 0, v[206:207]
	global_load_lds_dwordx4 v[198:199], off
	v_lshl_add_u64 v[198:199], s[6:7], 0, v[136:137]
	s_add_i32 m0, s48, 0x2000
	s_nop 0
	global_load_lds_dwordx4 v[198:199], off
	v_lshl_add_u64 v[198:199], s[52:53], 0, v[208:209]
	s_mov_b32 m0, s12
	s_nop 0
	global_load_lds_dwordx4 v[198:199], off
	s_mov_b32 m0, s13
	s_nop 0
	global_load_lds_dwordx4 v[200:201], off
	s_waitcnt vmcnt(9)
	s_waitcnt lgkmcnt(0)
	s_barrier
; #define PG8_STAGE(bufoff, gbase, voff) do { _Pragma("unroll") for (int _i = 0; _i < 2; ++_i) \
;         __builtin_amdgcn_global_load_lds((const unsigned*)((const char*)(gbase) + (voff)[_i]), (LAS unsigned*)(lds + (bufoff) + ldsw + _i * 8192), 16, 0, 0); } while (0)
; #define PG8_LDA(dst, b, h) do { _Pragma("unroll") for (int m = 0; m < 4; ++m) _Pragma("unroll") for (int k = 0; k < 2; ++k) dst[m][k] = *(const LAS bf16x8*)(lds + PG8_SA(b, h) + aoff + m * 2048 + k * 1024); } while (0)
; #define PG8_LDB(dst, b, h) do { _Pragma("unroll") for (int n = 0; n < 2; ++n) _Pragma("unroll") for (int k = 0; k < 2; ++k) dst[n][k] = *(const LAS bf16x8*)(lds + PG8_SB(b, h) + boff + n * 2048 + k * 1024); } while (0)
; #define PG8_MMA(ai, bj, At, Bt) do { __builtin_amdgcn_s_setprio(1); _Pragma("unroll") for (int m = 0; m < 4; ++m) _Pragma("unroll") for (int n = 0; n < 2; ++n) _Pragma("unroll") for (int k = 0; k < 2; ++k) \
;         acc[ai][bj][m][n] = __builtin_amdgcn_mfma_f32_16x16x32_bf16(Bt[n][k], At[m][k], acc[ai][bj][m][n], 0, 0, 0); __builtin_amdgcn_s_setprio(0); } while (0)
; #define PG8_WAIT_V(n) asm volatile("s_waitcnt vmcnt(" #n ")" ::: "memory")
; #define PG8_WAIT_L(n) asm volatile("s_waitcnt lgkmcnt(" #n ")" ::: "memory")
; #define PG8_BAR __builtin_amdgcn_s_barrier()
; #define PG8_SCHED __builtin_amdgcn_sched_barrier(0)
; template <class Epi, bool ALIGN_EPI>
; __device__ __forceinline__ void gemm_phase(LAS unsigned char* lds, const Gemm g, int G, int cid, const Epi& E) {
;     ...
;             PG8_WAIT_V(8); PG8_WAIT_L(0); PG8_BAR; PG8_MMA(1, 0, At, B0); PG8_MMA(1, 1, At, B1); PG8_BAR; PG8_SCHED;
;             PG8_LDB(B0, 1, 0); PG8_LDB(B1, 1, 1); PG8_SCHED; PG8_LDA(At, 1, 0); PG8_STAGE(PG8_SA(0, 1), a2 + hA, voffA);
;             PG8_WAIT_V(8); PG8_WAIT_L(0); PG8_BAR; PG8_MMA(0, 0, At, B0); PG8_MMA(0, 1, At, B1); PG8_BAR; PG8_SCHED;
	s_waitcnt lgkmcnt(0)
	v_mfma_f32_16x16x32_bf16 v[60:63], v[128:131], v[164:167], v[60:63]
	v_mfma_f32_16x16x32_bf16 v[56:59], v[140:143], v[164:167], v[56:59]
	v_mfma_f32_16x16x32_bf16 v[44:47], v[128:131], v[172:175], v[44:47]
	v_mfma_f32_16x16x32_bf16 v[40:43], v[140:143], v[172:175], v[40:43]
	v_mfma_f32_16x16x32_bf16 v[28:31], v[128:131], v[180:183], v[28:31]
	v_mfma_f32_16x16x32_bf16 v[24:27], v[140:143], v[180:183], v[24:27]
	v_mfma_f32_16x16x32_bf16 v[12:15], v[128:131], v[188:191], v[12:15]
	v_mfma_f32_16x16x32_bf16 v[8:11], v[140:143], v[188:191], v[8:11]
	v_mfma_f32_16x16x32_bf16 v[60:63], v[132:135], v[168:171], v[60:63]
	v_mfma_f32_16x16x32_bf16 v[56:59], v[144:147], v[168:171], v[56:59]
	v_mfma_f32_16x16x32_bf16 v[44:47], v[132:135], v[176:179], v[44:47]
	v_mfma_f32_16x16x32_bf16 v[40:43], v[144:147], v[176:179], v[40:43]
	v_mfma_f32_16x16x32_bf16 v[28:31], v[132:135], v[184:187], v[28:31]
	v_mfma_f32_16x16x32_bf16 v[24:27], v[144:147], v[184:187], v[24:27]
	v_mfma_f32_16x16x32_bf16 v[12:15], v[132:135], v[214:217], v[12:15]
	v_mfma_f32_16x16x32_bf16 v[8:11], v[144:147], v[214:217], v[8:11]
	v_mfma_f32_16x16x32_bf16 v[52:55], v[148:151], v[164:167], v[52:55]
	v_mfma_f32_16x16x32_bf16 v[48:51], v[156:159], v[164:167], v[48:51]
	v_mfma_f32_16x16x32_bf16 v[36:39], v[148:151], v[172:175], v[36:39]
	v_mfma_f32_16x16x32_bf16 v[32:35], v[156:159], v[172:175], v[32:35]
	v_mfma_f32_16x16x32_bf16 v[20:23], v[148:151], v[180:183], v[20:23]
	v_mfma_f32_16x16x32_bf16 v[16:19], v[156:159], v[180:183], v[16:19]
	v_mfma_f32_16x16x32_bf16 v[4:7], v[148:151], v[188:191], v[4:7]
	v_mfma_f32_16x16x32_bf16 v[0:3], v[156:159], v[188:191], v[0:3]
	v_mfma_f32_16x16x32_bf16 v[52:55], v[152:155], v[168:171], v[52:55]
	v_mfma_f32_16x16x32_bf16 v[48:51], v[160:163], v[168:171], v[48:51]
	v_mfma_f32_16x16x32_bf16 v[36:39], v[152:155], v[176:179], v[36:39]
	v_mfma_f32_16x16x32_bf16 v[32:35], v[160:163], v[176:179], v[32:35]
	v_mfma_f32_16x16x32_bf16 v[20:23], v[152:155], v[184:187], v[20:23]
	v_mfma_f32_16x16x32_bf16 v[16:19], v[160:163], v[184:187], v[16:19]
	v_mfma_f32_16x16x32_bf16 v[4:7], v[152:155], v[214:217], v[4:7]
	v_mfma_f32_16x16x32_bf16 v[0:3], v[160:163], v[214:217], v[0:3]
	s_barrier
	s_add_i32 s48, 0, 0x18000
	s_add_i32 s49, 0, 0x1c000
	v_add_u32_e32 v144, s48, v243
	v_add_u32_e32 v160, s49, v243
	ds_read_b128 v[128:131], v144
	ds_read_b128 v[132:135], v144 offset:1024
	ds_read_b128 v[140:143], v144 offset:2048
	ds_read_b128 v[144:147], v144 offset:3072
	ds_read_b128 v[148:151], v160
	ds_read_b128 v[152:155], v160 offset:1024
	ds_read_b128 v[156:159], v160 offset:2048
	ds_read_b128 v[160:163], v160 offset:3072
	s_add_u32 s6, s52, 0x160000
	s_addc_u32 s7, s53, 0
	s_mov_b32 m0, s54
	v_lshl_add_u64 v[218:219], s[6:7], 0, v[208:209]
	ds_read_b128 v[164:167], v245 offset:32768
	ds_read_b128 v[168:171], v245 offset:33792
	ds_read_b128 v[172:175], v245 offset:34816
	ds_read_b128 v[176:179], v245 offset:35840
	ds_read_b128 v[180:183], v245 offset:36864
	ds_read_b128 v[184:187], v245 offset:37888
	ds_read_b128 v[188:191], v245 offset:38912
	ds_read_b128 v[214:217], v245 offset:39936
	global_load_lds_dwordx4 v[218:219], off
	v_lshl_add_u64 v[218:219], s[6:7], 0, v[206:207]
	s_mov_b32 m0, s55
	s_nop 0
	global_load_lds_dwordx4 v[218:219], off
	s_waitcnt vmcnt(8)
	s_waitcnt lgkmcnt(0)
	s_barrier
	s_waitcnt lgkmcnt(0)
	v_mfma_f32_16x16x32_bf16 v[124:127], v[128:131], v[164:167], v[124:127]
	v_mfma_f32_16x16x32_bf16 v[120:123], v[140:143], v[164:167], v[120:123]
	v_mfma_f32_16x16x32_bf16 v[108:111], v[128:131], v[172:175], v[108:111]
	v_mfma_f32_16x16x32_bf16 v[104:107], v[140:143], v[172:175], v[104:107]
	v_mfma_f32_16x16x32_bf16 v[92:95], v[128:131], v[180:183], v[92:95]
	v_mfma_f32_16x16x32_bf16 v[88:91], v[140:143], v[180:183], v[88:91]
	v_mfma_f32_16x16x32_bf16 v[76:79], v[128:131], v[188:191], v[76:79]
	v_mfma_f32_16x16x32_bf16 v[72:75], v[140:143], v[188:191], v[72:75]
	v_mfma_f32_16x16x32_bf16 v[124:127], v[132:135], v[168:171], v[124:127]
	v_mfma_f32_16x16x32_bf16 v[120:123], v[144:147], v[168:171], v[120:123]
	v_mfma_f32_16x16x32_bf16 v[108:111], v[132:135], v[176:179], v[108:111]
	v_mfma_f32_16x16x32_bf16 v[104:107], v[144:147], v[176:179], v[104:107]
	v_mfma_f32_16x16x32_bf16 v[92:95], v[132:135], v[184:187], v[92:95]
	v_mfma_f32_16x16x32_bf16 v[88:91], v[144:147], v[184:187], v[88:91]
	v_mfma_f32_16x16x32_bf16 v[76:79], v[132:135], v[214:217], v[76:79]
	v_mfma_f32_16x16x32_bf16 v[72:75], v[144:147], v[214:217], v[72:75]
	v_mfma_f32_16x16x32_bf16 v[116:119], v[148:151], v[164:167], v[116:119]
	v_mfma_f32_16x16x32_bf16 v[112:115], v[156:159], v[164:167], v[112:115]
	v_mfma_f32_16x16x32_bf16 v[100:103], v[148:151], v[172:175], v[100:103]
	v_mfma_f32_16x16x32_bf16 v[96:99], v[156:159], v[172:175], v[96:99]
	v_mfma_f32_16x16x32_bf16 v[84:87], v[148:151], v[180:183], v[84:87]
	v_mfma_f32_16x16x32_bf16 v[80:83], v[156:159], v[180:183], v[80:83]
	v_mfma_f32_16x16x32_bf16 v[68:71], v[148:151], v[188:191], v[68:71]
	v_mfma_f32_16x16x32_bf16 v[64:67], v[156:159], v[188:191], v[64:67]
	v_mfma_f32_16x16x32_bf16 v[116:119], v[152:155], v[168:171], v[116:119]
	v_mfma_f32_16x16x32_bf16 v[112:115], v[160:163], v[168:171], v[112:115]
	v_mfma_f32_16x16x32_bf16 v[100:103], v[152:155], v[176:179], v[100:103]
	v_mfma_f32_16x16x32_bf16 v[96:99], v[160:163], v[176:179], v[96:99]
	v_mfma_f32_16x16x32_bf16 v[84:87], v[152:155], v[184:187], v[84:87]
	v_mfma_f32_16x16x32_bf16 v[80:83], v[160:163], v[184:187], v[80:83]
	v_mfma_f32_16x16x32_bf16 v[68:71], v[152:155], v[214:217], v[68:71]
	v_mfma_f32_16x16x32_bf16 v[64:67], v[160:163], v[214:217], v[64:67]
	s_barrier
; __device__ __forceinline__ unsigned cvt_pk_bf16(float lo, float hi) { unsigned r; asm volatile("v_cvt_pk_bf16_f32 %0, %1, %2" : "=v"(r) : "v"(lo), "v"(hi)); return r; }
; #define PG8_STAGE(bufoff, gbase, voff) do { _Pragma("unroll") for (int _i = 0; _i < 2; ++_i) \
;         __builtin_amdgcn_global_load_lds((const unsigned*)((const char*)(gbase) + (voff)[_i]), (LAS unsigned*)(lds + (bufoff) + ldsw + _i * 8192), 16, 0, 0); } while (0)
; #define PG8_BAR __builtin_amdgcn_s_barrier()
; template <class Epi, bool ALIGN_EPI>
; __device__ __forceinline__ void gemm_phase(LAS unsigned char* lds, const Gemm g, int G, int cid, const Epi& E) {
;     ...
;             PG8_LDA(At, 1, 1); PG8_STAGE(PG8_SB(1, 0), b3, voffB); PG8_STAGE(PG8_SB(1, 1), b3 + hB, voffB); PG8_STAGE(PG8_SA(1, 0), a3, voffA);
;             PG8_WAIT_V(8); PG8_WAIT_L(0); PG8_BAR; PG8_MMA(1, 0, At, B0); PG8_MMA(1, 1, At, B1); PG8_BAR; PG8_SCHED;
;         }
;     __device__ __forceinline__ void operator()(const f32x4 (&acc)[2][2][4][2], const Unit& u, int wr, int wc, int fr, int fq, const LAS float*) const {
;     ...
;             for (int m = m0; m < m0 + MB; ++m) { const float* xr = Xs + (size_t)(row0 + ai * HALF + m * 16) * DM + col0;
; #pragma unroll
;                 for (int bj = 0; bj < 2; ++bj) { xo[m][bj][0] = *(const f32x4*)(xr + bj * HALF); xo[m][bj][1] = *(const f32x4*)(xr + bj * HALF + 4); } }
; #pragma unroll
;             for (int m = m0; m < m0 + MB; ++m) { const int row = row0 + ai * HALF + m * 16; float ss = 0.f;
;                 float* xr = X + (size_t)row * DM + col0; bf16_t* xb = XB + (size_t)row * ALD + col0;
; #pragma unroll
;                 for (int bj = 0; bj < 2; ++bj) { f32x4 x0 = xo[m][bj][0], x1 = xo[m][bj][1];
;                     if (HB) { x0 += (acc[ai][bj][m][0] + bv[bj][0]) * sv[bj][0]; x1 += (acc[ai][bj][m][1] + bv[bj][1]) * sv[bj][1]; } else { x0 += acc[ai][bj][m][0]; x1 += acc[ai][bj][m][1]; }
;                     *(f32x4*)(xr + bj * HALF) = x0; *(f32x4*)(xr + bj * HALF + 4) = x1;
;                     ss += (x0[0] * x0[0] + x0[1] * x0[1]) + (x0[2] * x0[2] + x0[3] * x0[3]) + (x1[0] * x1[0] + x1[1] * x1[1]) + (x1[2] * x1[2] + x1[3] * x1[3]);
;                     u32x4 w; w.x = cvt_pk_bf16(x0[0], x0[1]); w.y = cvt_pk_bf16(x0[2], x0[3]); w.z = cvt_pk_bf16(x1[0], x1[1]); w.w = cvt_pk_bf16(x1[2], x1[3]);
;                     if (feeds) *(u32x4*)(xb + bj * HALF) = w; }
	s_add_u32 s6, s50, 0x40000
	s_addc_u32 s7, s51, 0
	s_add_i32 s48, s48, s25
	v_lshl_add_u64 v[218:219], s[6:7], 0, v[138:139]
	s_mov_b32 m0, s48
	ds_read_b128 v[164:167], v245 offset:49152
	ds_read_b128 v[168:171], v245 offset:50176
	ds_read_b128 v[172:175], v245 offset:51200
	ds_read_b128 v[176:179], v245 offset:52224
	ds_read_b128 v[180:183], v245 offset:53248
	ds_read_b128 v[184:187], v245 offset:54272
	ds_read_b128 v[188:191], v245 offset:55296
	ds_read_b128 v[214:217], v245 offset:56320
	global_load_lds_dwordx4 v[218:219], off
	s_add_i32 m0, s48, 0x2000
	v_lshl_add_u64 v[218:219], s[6:7], 0, v[136:137]
	s_add_u32 s6, s50, 0x42000
	s_addc_u32 s7, s51, 0
	s_add_i32 s48, s49, s25
	global_load_lds_dwordx4 v[218:219], off
	v_lshl_add_u64 v[218:219], s[6:7], 0, v[138:139]
	s_mov_b32 m0, s48
	v_lshl_add_u64 v[198:199], v[198:199], 0, s[36:37]
	global_load_lds_dwordx4 v[218:219], off
	v_lshl_add_u64 v[218:219], s[6:7], 0, v[136:137]
	s_add_i32 m0, s48, 0x2000
	s_nop 0
	global_load_lds_dwordx4 v[218:219], off
	s_mov_b32 m0, s57
	s_nop 0
	global_load_lds_dwordx4 v[198:199], off
	v_lshl_add_u64 v[198:199], v[200:201], 0, s[36:37]
	s_mov_b32 m0, s58
	s_nop 0
	global_load_lds_dwordx4 v[198:199], off
	s_waitcnt vmcnt(8)
	s_waitcnt lgkmcnt(0)
	s_barrier
	s_waitcnt lgkmcnt(0)
	v_mfma_f32_16x16x32_bf16 v[60:63], v[128:131], v[164:167], v[60:63]
	v_mfma_f32_16x16x32_bf16 v[56:59], v[140:143], v[164:167], v[56:59]
	v_mfma_f32_16x16x32_bf16 v[44:47], v[128:131], v[172:175], v[44:47]
	v_mfma_f32_16x16x32_bf16 v[40:43], v[140:143], v[172:175], v[40:43]
	v_mfma_f32_16x16x32_bf16 v[28:31], v[128:131], v[180:183], v[28:31]
	v_mfma_f32_16x16x32_bf16 v[24:27], v[140:143], v[180:183], v[24:27]
	v_mfma_f32_16x16x32_bf16 v[12:15], v[128:131], v[188:191], v[12:15]
	v_mfma_f32_16x16x32_bf16 v[8:11], v[140:143], v[188:191], v[8:11]
	v_mfma_f32_16x16x32_bf16 v[60:63], v[132:135], v[168:171], v[60:63]
	v_mfma_f32_16x16x32_bf16 v[56:59], v[144:147], v[168:171], v[56:59]
	v_mfma_f32_16x16x32_bf16 v[44:47], v[132:135], v[176:179], v[44:47]
	v_mfma_f32_16x16x32_bf16 v[40:43], v[144:147], v[176:179], v[40:43]
	v_mfma_f32_16x16x32_bf16 v[28:31], v[132:135], v[184:187], v[28:31]
	v_mfma_f32_16x16x32_bf16 v[24:27], v[144:147], v[184:187], v[24:27]
	v_mfma_f32_16x16x32_bf16 v[12:15], v[132:135], v[214:217], v[12:15]
	v_mfma_f32_16x16x32_bf16 v[8:11], v[144:147], v[214:217], v[8:11]
	v_mfma_f32_16x16x32_bf16 v[52:55], v[148:151], v[164:167], v[52:55]
	v_mfma_f32_16x16x32_bf16 v[48:51], v[156:159], v[164:167], v[48:51]
	v_mfma_f32_16x16x32_bf16 v[36:39], v[148:151], v[172:175], v[36:39]
	v_mfma_f32_16x16x32_bf16 v[32:35], v[156:159], v[172:175], v[32:35]
	v_mfma_f32_16x16x32_bf16 v[20:23], v[148:151], v[180:183], v[20:23]
	v_mfma_f32_16x16x32_bf16 v[16:19], v[156:159], v[180:183], v[16:19]
	v_mfma_f32_16x16x32_bf16 v[4:7], v[148:151], v[188:191], v[4:7]
	v_mfma_f32_16x16x32_bf16 v[0:3], v[156:159], v[188:191], v[0:3]
	v_mfma_f32_16x16x32_bf16 v[52:55], v[152:155], v[168:171], v[52:55]
	v_mfma_f32_16x16x32_bf16 v[48:51], v[160:163], v[168:171], v[48:51]
	v_mfma_f32_16x16x32_bf16 v[36:39], v[152:155], v[176:179], v[36:39]
	v_mfma_f32_16x16x32_bf16 v[32:35], v[160:163], v[176:179], v[32:35]
	v_mfma_f32_16x16x32_bf16 v[20:23], v[152:155], v[184:187], v[20:23]
	v_mfma_f32_16x16x32_bf16 v[16:19], v[160:163], v[184:187], v[16:19]
	v_mfma_f32_16x16x32_bf16 v[4:7], v[152:155], v[214:217], v[4:7]
	v_mfma_f32_16x16x32_bf16 v[0:3], v[160:163], v[214:217], v[0:3]
	s_barrier
	s_add_i32 s79, s79, 2
	s_add_u32 s77, s77, 0x80000
	s_addc_u32 s78, s78, 0
	s_cmpk_gt_u32 s79, 0x55
	s_mov_b64 s[48:49], s[40:41]
	s_cbranch_scc0 .LBB0_927
	v_lshl_or_b32 v214, s74, 8, v244
	v_lshl_add_u32 v216, s75, 8, v197
	v_ashrrev_i32_e32 v215, 31, v214
	v_lshlrev_b64 v[198:199], 2, v[214:215]
	v_ashrrev_i32_e32 v217, 31, v216
	v_or_b32_e32 v226, 16, v216
	v_lshl_add_u64 v[218:219], s[82:83], 0, v[198:199]
	v_lshlrev_b64 v[200:201], 13, v[216:217]
	v_ashrrev_i32_e32 v227, 31, v226
	v_or_b32_e32 v222, 32, v216
	v_or_b32_e32 v220, 48, v216
	v_lshl_add_u64 v[128:129], v[218:219], 0, v[200:201]
	v_lshlrev_b64 v[230:231], 13, v[226:227]
	v_ashrrev_i32_e32 v223, 31, v222
	v_ashrrev_i32_e32 v221, 31, v220
	global_load_dwordx4 v[188:191], v[128:129], off offset:16
	global_load_dwordx4 v[246:249], v[128:129], off
	global_load_dwordx4 v[180:183], v[128:129], off offset:528
	global_load_dwordx4 v[184:187], v[128:129], off offset:512
	v_lshl_add_u64 v[128:129], v[218:219], 0, v[230:231]
	v_lshlrev_b64 v[228:229], 13, v[222:223]
	v_lshlrev_b64 v[224:225], 13, v[220:221]
	global_load_dwordx4 v[172:175], v[128:129], off offset:16
	global_load_dwordx4 v[176:179], v[128:129], off
	global_load_dwordx4 v[164:167], v[128:129], off offset:528
	global_load_dwordx4 v[168:171], v[128:129], off offset:512
	v_lshl_add_u64 v[128:129], v[218:219], 0, v[228:229]
	v_lshl_add_u64 v[132:133], v[218:219], 0, v[224:225]
	global_load_dwordx4 v[156:159], v[128:129], off offset:16
	global_load_dwordx4 v[160:163], v[128:129], off
	global_load_dwordx4 v[148:151], v[128:129], off offset:528
	global_load_dwordx4 v[152:155], v[128:129], off offset:512
	global_load_dwordx4 v[140:143], v[132:133], off offset:16
	global_load_dwordx4 v[144:147], v[132:133], off
	s_nop 0
	global_load_dwordx4 v[128:131], v[132:133], off offset:528
	s_nop 0
	global_load_dwordx4 v[132:135], v[132:133], off offset:512
	v_lshl_add_u64 v[200:201], s[82:83], 0, v[200:201]
	v_lshl_add_u64 v[234:235], v[200:201], 0, v[198:199]
	v_mov_b64_e32 v[198:199], s[4:5]
	v_mad_i64_i32 v[198:199], s[6:7], v216, s66, v[198:199]
	v_lshl_add_u64 v[232:233], v[214:215], 1, v[198:199]
	s_and_b64 vcc, exec, s[28:29]
	s_waitcnt vmcnt(12)
	v_pk_add_f32 v[122:123], v[122:123], v[190:191]
	v_pk_add_f32 v[126:127], v[126:127], v[248:249]
	v_pk_add_f32 v[124:125], v[124:125], v[246:247]
	v_pk_add_f32 v[120:121], v[120:121], v[188:189]
	global_store_dwordx4 v[234:235], v[124:127], off
	global_store_dwordx4 v[234:235], v[120:123], off offset:16
	v_cvt_pk_bf16_f32 v188, v124, v125
	v_cvt_pk_bf16_f32 v189, v126, v127
	v_cvt_pk_bf16_f32 v190, v120, v121
	v_cvt_pk_bf16_f32 v191, v122, v123
	s_cbranch_vccz .LBB0_930
	global_store_dwordx4 v[232:233], v[188:191], off
